# W_o / FFN2 epilogue: residual pieces loaded and stored row-major (both lines of a row back to back)
# baseline (speedup 1.0000x reference)
.LBB0_128:
	s_setprio 1
	s_add_u32 s98, s42, s27
	s_addc_u32 s99, s43, 0
	s_add_u32 s98, s98, 0x80
	s_addc_u32 s99, s99, 0
	ds_read_b128 v[132:135], v127 offset:16384
	ds_read_b128 v[140:143], v129
	ds_read_b128 v[152:155], v127 offset:18432
	ds_read_b128 v[160:163], v127 offset:20480
	ds_read_b128 v[164:167], v127 offset:22528
	ds_read_b128 v[144:147], v129 offset:2048
	ds_read_b128 v[148:151], v129 offset:4096
	ds_read_b128 v[156:159], v129 offset:6144
	s_add_u32 m0, s100, 0x8000
	s_waitcnt lgkmcnt(6)
	v_mfma_f32_16x16x32_bf16 v[34:37], v[132:135], v[140:143], v[34:37]
	global_load_lds_dwordx4 v194, s[98:99]
	s_waitcnt lgkmcnt(5)
	v_mfma_f32_16x16x32_bf16 v[94:97], v[152:155], v[140:143], v[94:97]
	ds_read_b128 v[198:201], v128
	s_add_u32 m0, s100, 0xc000
	s_waitcnt lgkmcnt(5)
	v_mfma_f32_16x16x32_bf16 v[38:41], v[160:163], v[140:143], v[38:41]
	global_load_lds_dwordx4 v195, s[98:99]
	s_waitcnt lgkmcnt(4)
	v_mfma_f32_16x16x32_bf16 v[90:93], v[164:167], v[140:143], v[90:93]
	ds_read_b128 v[140:143], v128 offset:2048
	s_add_u32 m0, s100, 0x9000
	s_waitcnt lgkmcnt(4)
	v_mfma_f32_16x16x32_bf16 v[42:45], v[132:135], v[144:147], v[42:45]
	global_load_lds_dwordx4 v196, s[98:99]
	v_mfma_f32_16x16x32_bf16 v[86:89], v[152:155], v[144:147], v[86:89]
	ds_read_b128 v[210:213], v128 offset:4096
	s_add_u32 m0, s100, 0xd000
	v_mfma_f32_16x16x32_bf16 v[46:49], v[160:163], v[144:147], v[46:49]
	global_load_lds_dwordx4 v197, s[98:99]
	v_mfma_f32_16x16x32_bf16 v[82:85], v[164:167], v[144:147], v[82:85]
	ds_read_b128 v[144:147], v128 offset:6144
	s_add_u32 m0, s100, 0xa000
	s_waitcnt lgkmcnt(5)
	v_mfma_f32_16x16x32_bf16 v[50:53], v[132:135], v[148:151], v[50:53]
	global_load_lds_dwordx4 v202, s[98:99]
	v_mfma_f32_16x16x32_bf16 v[78:81], v[152:155], v[148:151], v[78:81]
	ds_read_b128 v[222:225], v130 offset:16384
	s_add_u32 m0, s100, 0xe000
	v_mfma_f32_16x16x32_bf16 v[54:57], v[160:163], v[148:151], v[54:57]
	global_load_lds_dwordx4 v203, s[98:99]
	v_mfma_f32_16x16x32_bf16 v[70:73], v[164:167], v[148:151], v[70:73]
	ds_read_b128 v[148:151], v130 offset:18432
	s_add_u32 m0, s100, 0xb000
	s_waitcnt lgkmcnt(6)
	v_mfma_f32_16x16x32_bf16 v[58:61], v[132:135], v[156:159], v[58:61]
	global_load_lds_dwordx4 v204, s[98:99]
	v_mfma_f32_16x16x32_bf16 v[66:69], v[152:155], v[156:159], v[66:69]
	ds_read_b128 v[152:155], v130 offset:20480
	s_add_u32 m0, s100, 0xf000
	v_mfma_f32_16x16x32_bf16 v[62:65], v[160:163], v[156:159], v[62:65]
	global_load_lds_dwordx4 v205, s[98:99]
	v_mfma_f32_16x16x32_bf16 v[74:77], v[164:167], v[156:159], v[74:77]
	ds_read_b128 v[156:159], v130 offset:22528
	s_waitcnt lgkmcnt(3)
	v_mfma_f32_16x16x32_bf16 v[34:37], v[222:225], v[198:201], v[34:37]
	s_waitcnt lgkmcnt(2)
	v_mfma_f32_16x16x32_bf16 v[94:97], v[148:151], v[198:201], v[94:97]
	s_waitcnt lgkmcnt(1)
	v_mfma_f32_16x16x32_bf16 v[38:41], v[152:155], v[198:201], v[38:41]
	s_waitcnt lgkmcnt(0)
	v_mfma_f32_16x16x32_bf16 v[90:93], v[156:159], v[198:201], v[90:93]
	v_mfma_f32_16x16x32_bf16 v[42:45], v[222:225], v[140:143], v[42:45]
	v_mfma_f32_16x16x32_bf16 v[86:89], v[148:151], v[140:143], v[86:89]
	v_mfma_f32_16x16x32_bf16 v[46:49], v[152:155], v[140:143], v[46:49]
	v_mfma_f32_16x16x32_bf16 v[82:85], v[156:159], v[140:143], v[82:85]
	v_mfma_f32_16x16x32_bf16 v[50:53], v[222:225], v[210:213], v[50:53]
	v_mfma_f32_16x16x32_bf16 v[78:81], v[148:151], v[210:213], v[78:81]
	v_mfma_f32_16x16x32_bf16 v[54:57], v[152:155], v[210:213], v[54:57]
	v_mfma_f32_16x16x32_bf16 v[70:73], v[156:159], v[210:213], v[70:73]
	v_mfma_f32_16x16x32_bf16 v[58:61], v[222:225], v[144:147], v[58:61]
	v_mfma_f32_16x16x32_bf16 v[66:69], v[148:151], v[144:147], v[66:69]
	v_mfma_f32_16x16x32_bf16 v[62:65], v[152:155], v[144:147], v[62:65]
	v_mfma_f32_16x16x32_bf16 v[74:77], v[156:159], v[144:147], v[74:77]
	s_waitcnt vmcnt(0)
	s_setprio 0
	s_waitcnt lgkmcnt(0)
	s_barrier
	s_setprio 1
	s_add_u32 s98, s98, 0x80
	s_addc_u32 s99, s99, 0
	ds_read_b128 v[26:29], v127 offset:49152
	ds_read_b128 v[10:13], v129 offset:32768
	ds_read_b128 v[30:33], v127 offset:51200
	ds_read_b128 v[148:151], v127 offset:53248
	ds_read_b128 v[152:155], v127 offset:55296
	ds_read_b128 v[18:21], v129 offset:34816
	ds_read_b128 v[140:143], v129 offset:36864
	ds_read_b128 v[144:147], v129 offset:38912
	s_add_u32 m0, s100, 0x0
	s_waitcnt lgkmcnt(6)
	v_mfma_f32_16x16x32_bf16 v[34:37], v[26:29], v[10:13], v[34:37]
	global_load_lds_dwordx4 v194, s[98:99]
	s_waitcnt lgkmcnt(5)
	v_mfma_f32_16x16x32_bf16 v[94:97], v[30:33], v[10:13], v[94:97]
	ds_read_b128 v[156:159], v128 offset:32768
	s_add_u32 m0, s100, 0x4000
	s_waitcnt lgkmcnt(5)
	v_mfma_f32_16x16x32_bf16 v[38:41], v[148:151], v[10:13], v[38:41]
	global_load_lds_dwordx4 v195, s[98:99]
	s_waitcnt lgkmcnt(4)
	v_mfma_f32_16x16x32_bf16 v[90:93], v[152:155], v[10:13], v[90:93]
	ds_read_b128 v[164:167], v128 offset:34816
	s_add_u32 m0, s100, 0x1000
	s_waitcnt lgkmcnt(4)
	v_mfma_f32_16x16x32_bf16 v[42:45], v[26:29], v[18:21], v[42:45]
	global_load_lds_dwordx4 v196, s[98:99]
	v_mfma_f32_16x16x32_bf16 v[86:89], v[30:33], v[18:21], v[86:89]
	ds_read_b128 v[198:201], v128 offset:36864
	s_add_u32 m0, s100, 0x5000
	v_mfma_f32_16x16x32_bf16 v[46:49], v[148:151], v[18:21], v[46:49]
	global_load_lds_dwordx4 v197, s[98:99]
	v_mfma_f32_16x16x32_bf16 v[82:85], v[152:155], v[18:21], v[82:85]
	ds_read_b128 v[210:213], v128 offset:38912
	s_add_u32 m0, s100, 0x2000
	s_waitcnt lgkmcnt(5)
	v_mfma_f32_16x16x32_bf16 v[50:53], v[26:29], v[140:143], v[50:53]
	global_load_lds_dwordx4 v202, s[98:99]
	v_mfma_f32_16x16x32_bf16 v[78:81], v[30:33], v[140:143], v[78:81]
	ds_read_b128 v[222:225], v130 offset:49152
	s_add_u32 m0, s100, 0x6000
	v_mfma_f32_16x16x32_bf16 v[54:57], v[148:151], v[140:143], v[54:57]
	global_load_lds_dwordx4 v203, s[98:99]
	v_mfma_f32_16x16x32_bf16 v[70:73], v[152:155], v[140:143], v[70:73]
	ds_read_b128 v[140:143], v130 offset:51200
	s_add_u32 m0, s100, 0x3000
	s_waitcnt lgkmcnt(6)
	v_mfma_f32_16x16x32_bf16 v[58:61], v[26:29], v[144:147], v[58:61]
	global_load_lds_dwordx4 v204, s[98:99]
	v_mfma_f32_16x16x32_bf16 v[66:69], v[30:33], v[144:147], v[66:69]
	ds_read_b128 v[230:233], v130 offset:53248
	s_add_u32 m0, s100, 0x7000
	v_mfma_f32_16x16x32_bf16 v[62:65], v[148:151], v[144:147], v[62:65]
	global_load_lds_dwordx4 v205, s[98:99]
	v_mfma_f32_16x16x32_bf16 v[74:77], v[152:155], v[144:147], v[74:77]
	ds_read_b128 v[144:147], v130 offset:55296
	s_waitcnt lgkmcnt(3)
	v_mfma_f32_16x16x32_bf16 v[34:37], v[222:225], v[156:159], v[34:37]
	s_waitcnt lgkmcnt(2)
	v_mfma_f32_16x16x32_bf16 v[94:97], v[140:143], v[156:159], v[94:97]
	s_waitcnt lgkmcnt(1)
	v_mfma_f32_16x16x32_bf16 v[38:41], v[230:233], v[156:159], v[38:41]
	s_waitcnt lgkmcnt(0)
	v_mfma_f32_16x16x32_bf16 v[90:93], v[144:147], v[156:159], v[90:93]
	v_mfma_f32_16x16x32_bf16 v[42:45], v[222:225], v[164:167], v[42:45]
	v_mfma_f32_16x16x32_bf16 v[86:89], v[140:143], v[164:167], v[86:89]
	v_mfma_f32_16x16x32_bf16 v[46:49], v[230:233], v[164:167], v[46:49]
	v_mfma_f32_16x16x32_bf16 v[82:85], v[144:147], v[164:167], v[82:85]
	v_mfma_f32_16x16x32_bf16 v[50:53], v[222:225], v[198:201], v[50:53]
	v_mfma_f32_16x16x32_bf16 v[78:81], v[140:143], v[198:201], v[78:81]
	v_mfma_f32_16x16x32_bf16 v[54:57], v[230:233], v[198:201], v[54:57]
	v_mfma_f32_16x16x32_bf16 v[70:73], v[144:147], v[198:201], v[70:73]
	v_mfma_f32_16x16x32_bf16 v[58:61], v[222:225], v[210:213], v[58:61]
	v_mfma_f32_16x16x32_bf16 v[66:69], v[140:143], v[210:213], v[66:69]
	v_mfma_f32_16x16x32_bf16 v[62:65], v[230:233], v[210:213], v[62:65]
	v_mfma_f32_16x16x32_bf16 v[74:77], v[144:147], v[210:213], v[74:77]
	s_waitcnt vmcnt(0)
	s_setprio 0
	s_add_i32 s8, s8, 2
	s_add_u32 s42, s42, 0x100
	s_addc_u32 s43, s43, 0
	s_cmp_lt_u32 s8, 40
	s_waitcnt lgkmcnt(0)
	s_barrier
	s_cbranch_scc1 .LBB0_128
	v_mov_b32_e32 v2, v194
	v_mov_b32_e32 v3, v195
	v_mov_b32_e32 v4, v196
	v_mov_b32_e32 v5, v197
	v_mov_b32_e32 v6, v202
	v_mov_b32_e32 v7, v203
	v_mov_b32_e32 v8, v204
	v_mov_b32_e32 v9, v205
	s_add_u32 s98, s42, s27
	s_addc_u32 s99, s43, 0
	s_add_u32 s98, s98, 0x80
	s_addc_u32 s99, s99, 0
	s_add_i32 s8, s11, s2
	s_cmpk_lt_u32 s8, 0x100
	s_cselect_b32 s10, s8, s11
	s_lshr_b32 s9, s10, 3
	s_and_b32 s9, s9, 0x1fffff8
	s_add_i32 s9, s9, s21
	s_and_b32 s11, s10, 7
	s_or_b32 s9, s9, s11
	v_mov_b32_e32 v0, v169
	s_lshl_b32 s9, s9, 7
	s_movk_i32 s11, 0xb00
	v_lshrrev_b32_e32 v98, 3, v0
	v_add_u32_e32 v98, s9, v98
	v_lshlrev_b32_e32 v0, 3, v0
	v_mul_lo_u32 v98, v98, s11
	s_lshl_b32 s10, s10, 4
	v_and_or_b32 v0, v0, 56, v98
	v_mov_b32_e32 v98, v169
	s_and_b32 s10, s10, 0x380
	s_cmpk_gt_u32 s8, 0xff
	s_cselect_b32 s101, 1, 0
	v_lshrrev_b32_e32 v99, 3, v98
	v_add_u32_e32 v99, s10, v99
	v_lshlrev_b32_e32 v98, 3, v98
	v_mul_lo_u32 v99, v99, s11
	v_and_or_b32 v164, v98, 56, v99
	v_add_u32_e32 v114, 0x16000, v0
	v_add_u32_e32 v124, 0x2c000, v0
	v_add_u32_e32 v136, 0x42000, v0
	v_add_u32_e32 v174, 0x16000, v164
	v_add_u32_e32 v176, 0x2c000, v164
	v_add_u32_e32 v178, 0x42000, v164
	s_setprio 1
	ds_read_b128 v[98:101], v127 offset:16384
	ds_read_b128 v[102:105], v129
	ds_read_b128 v[110:113], v127 offset:18432
	ds_read_b128 v[144:147], v127 offset:20480
	ds_read_b128 v[148:151], v127 offset:22528
	ds_read_b128 v[106:109], v129 offset:2048
	ds_read_b128 v[132:135], v129 offset:4096
	ds_read_b128 v[140:143], v129 offset:6144
	v_lshrrev_b32_e32 v14, 3, v169
	v_and_b32_e32 v15, 3, v14
	v_bfe_u32 v16, v14, 4, 1
	v_lshl_or_b32 v15, v16, 2, v15
	v_bfe_u32 v16, v14, 2, 1
	v_lshl_or_b32 v15, v16, 3, v15
	v_bfe_u32 v16, v14, 3, 1
	v_lshl_or_b32 v15, v16, 4, v15
	v_sub_u32_e32 v15, v15, v14
	v_mul_i32_i24_e32 v15, 0xb00, v15
	v_and_b32_e32 v14, 7, v14
	v_lshlrev_b32_e32 v14, 3, v14
	v_xor_b32_e32 v0, v0, v14
	v_add_u32_e32 v164, v164, v15
	v_xor_b32_e32 v164, v164, v14
	v_xor_b32_e32 v114, v114, v14
	v_add_u32_e32 v174, v174, v15
	v_xor_b32_e32 v174, v174, v14
	v_xor_b32_e32 v124, v124, v14
	v_add_u32_e32 v176, v176, v15
	v_xor_b32_e32 v176, v176, v14
	v_xor_b32_e32 v136, v136, v14
	v_add_u32_e32 v178, v178, v15
	v_xor_b32_e32 v178, v178, v14
	v_readlane_b32 s14, v254, 33
	v_readlane_b32 s15, v254, 34
	v_mov_b32_e32 v165, v1
	v_mov_b32_e32 v115, v1
	v_mov_b32_e32 v175, v1
	v_mov_b32_e32 v125, v1
	v_mov_b32_e32 v177, v1
	v_mov_b32_e32 v137, v1
	v_mov_b32_e32 v179, v1
	v_lshl_add_u64 v[180:181], v[0:1], 1, s[14:15]
	v_lshl_add_u64 v[186:187], v[164:165], 1, s[38:39]
	v_lshl_add_u64 v[114:115], v[114:115], 1, s[14:15]
	v_lshl_add_u64 v[174:175], v[174:175], 1, s[38:39]
	v_lshl_add_u64 v[188:189], v[124:125], 1, s[14:15]
	v_lshl_add_u64 v[176:177], v[176:177], 1, s[38:39]
	v_lshl_add_u64 v[136:137], v[136:137], 1, s[14:15]
	v_lshl_add_u64 v[178:179], v[178:179], 1, s[38:39]
	s_add_u32 m0, s100, 0x8000
	s_waitcnt lgkmcnt(6)
	v_mfma_f32_16x16x32_bf16 v[152:155], v[98:101], v[102:105], v[34:37]
	global_load_lds_dwordx4 v2, s[98:99]
	s_waitcnt lgkmcnt(5)
	v_mfma_f32_16x16x32_bf16 v[94:97], v[110:113], v[102:105], v[94:97]
	ds_read_b128 v[156:159], v128
	s_add_u32 m0, s100, 0xc000
	s_waitcnt lgkmcnt(5)
	v_mfma_f32_16x16x32_bf16 v[160:163], v[144:147], v[102:105], v[38:41]
	global_load_lds_dwordx4 v3, s[98:99]
	s_waitcnt lgkmcnt(4)
	v_mfma_f32_16x16x32_bf16 v[90:93], v[148:151], v[102:105], v[90:93]
	ds_read_b128 v[102:105], v128 offset:2048
	s_add_u32 m0, s100, 0x9000
	s_waitcnt lgkmcnt(4)
	v_mfma_f32_16x16x32_bf16 v[164:167], v[98:101], v[106:109], v[42:45]
	global_load_lds_dwordx4 v4, s[98:99]
	v_mfma_f32_16x16x32_bf16 v[86:89], v[110:113], v[106:109], v[86:89]
	ds_read_b128 v[194:197], v128 offset:4096
	s_add_u32 m0, s100, 0xd000
	v_mfma_f32_16x16x32_bf16 v[198:201], v[144:147], v[106:109], v[46:49]
	global_load_lds_dwordx4 v5, s[98:99]
	v_mfma_f32_16x16x32_bf16 v[82:85], v[148:151], v[106:109], v[82:85]
	ds_read_b128 v[106:109], v128 offset:6144
	s_add_u32 m0, s100, 0xa000
	s_waitcnt lgkmcnt(5)
	v_mfma_f32_16x16x32_bf16 v[202:205], v[98:101], v[132:135], v[50:53]
	global_load_lds_dwordx4 v6, s[98:99]
	v_mfma_f32_16x16x32_bf16 v[78:81], v[110:113], v[132:135], v[78:81]
	ds_read_b128 v[206:209], v130 offset:16384
	s_add_u32 m0, s100, 0xe000
	v_mfma_f32_16x16x32_bf16 v[210:213], v[144:147], v[132:135], v[54:57]
	global_load_lds_dwordx4 v7, s[98:99]
	v_mfma_f32_16x16x32_bf16 v[70:73], v[148:151], v[132:135], v[70:73]
	ds_read_b128 v[132:135], v130 offset:18432
	s_add_u32 m0, s100, 0xb000
	s_waitcnt lgkmcnt(6)
	v_mfma_f32_16x16x32_bf16 v[98:101], v[98:101], v[140:143], v[58:61]
	global_load_lds_dwordx4 v8, s[98:99]
	v_mfma_f32_16x16x32_bf16 v[66:69], v[110:113], v[140:143], v[66:69]
	ds_read_b128 v[110:113], v130 offset:20480
	s_add_u32 m0, s100, 0xf000
	v_mfma_f32_16x16x32_bf16 v[144:147], v[144:147], v[140:143], v[62:65]
	global_load_lds_dwordx4 v9, s[98:99]
	v_mfma_f32_16x16x32_bf16 v[74:77], v[148:151], v[140:143], v[74:77]
	ds_read_b128 v[140:143], v130 offset:22528
	s_waitcnt lgkmcnt(3)
	v_mfma_f32_16x16x32_bf16 v[148:151], v[206:209], v[156:159], v[152:155]
	s_waitcnt lgkmcnt(2)
	v_mfma_f32_16x16x32_bf16 v[94:97], v[132:135], v[156:159], v[94:97]
	s_waitcnt lgkmcnt(1)
	v_mfma_f32_16x16x32_bf16 v[152:155], v[110:113], v[156:159], v[160:163]
	s_waitcnt lgkmcnt(0)
	v_mfma_f32_16x16x32_bf16 v[90:93], v[140:143], v[156:159], v[90:93]
	v_mfma_f32_16x16x32_bf16 v[156:159], v[206:209], v[102:105], v[164:167]
	v_mfma_f32_16x16x32_bf16 v[86:89], v[132:135], v[102:105], v[86:89]
	v_mfma_f32_16x16x32_bf16 v[160:163], v[110:113], v[102:105], v[198:201]
	v_mfma_f32_16x16x32_bf16 v[82:85], v[140:143], v[102:105], v[82:85]
	v_mfma_f32_16x16x32_bf16 v[102:105], v[206:209], v[194:197], v[202:205]
	v_mfma_f32_16x16x32_bf16 v[78:81], v[132:135], v[194:197], v[78:81]
	v_mfma_f32_16x16x32_bf16 v[164:167], v[110:113], v[194:197], v[210:213]
	v_mfma_f32_16x16x32_bf16 v[70:73], v[140:143], v[194:197], v[70:73]
	v_mfma_f32_16x16x32_bf16 v[98:101], v[206:209], v[106:109], v[98:101]
	v_mfma_f32_16x16x32_bf16 v[66:69], v[132:135], v[106:109], v[66:69]
	v_mfma_f32_16x16x32_bf16 v[110:113], v[110:113], v[106:109], v[144:147]
	v_mfma_f32_16x16x32_bf16 v[74:77], v[140:143], v[106:109], v[74:77]
	s_waitcnt vmcnt(0)
	s_setprio 0
	s_waitcnt lgkmcnt(0)
	s_barrier
	s_setprio 1
	ds_read_b128 v[26:29], v127 offset:49152
	ds_read_b128 v[10:13], v129 offset:32768
	ds_read_b128 v[30:33], v127 offset:51200
	ds_read_b128 v[132:135], v127 offset:53248
	ds_read_b128 v[140:143], v127 offset:55296
	ds_read_b128 v[18:21], v129 offset:34816
	ds_read_b128 v[106:109], v129 offset:36864
	ds_read_b128 v[122:125], v129 offset:38912
	s_add_u32 m0, s100, 0x0
	s_waitcnt lgkmcnt(6)
	v_mfma_f32_16x16x32_bf16 v[144:147], v[26:29], v[10:13], v[148:151]
	global_load_lds_dwordx4 v[180:181], off
	s_waitcnt lgkmcnt(5)
	v_mfma_f32_16x16x32_bf16 v[94:97], v[30:33], v[10:13], v[94:97]
	ds_read_b128 v[148:151], v128 offset:32768
	s_add_u32 m0, s100, 0x4000
	s_waitcnt lgkmcnt(5)
	v_mfma_f32_16x16x32_bf16 v[152:155], v[132:135], v[10:13], v[152:155]
	global_load_lds_dwordx4 v[186:187], off
	s_waitcnt lgkmcnt(4)
	v_mfma_f32_16x16x32_bf16 v[90:93], v[140:143], v[10:13], v[90:93]
	ds_read_b128 v[194:197], v128 offset:34816
	s_add_u32 m0, s100, 0x1000
	s_waitcnt lgkmcnt(4)
	v_mfma_f32_16x16x32_bf16 v[156:159], v[26:29], v[18:21], v[156:159]
	global_load_lds_dwordx4 v[114:115], off
	v_mfma_f32_16x16x32_bf16 v[86:89], v[30:33], v[18:21], v[86:89]
	ds_read_b128 v[198:201], v128 offset:36864
	s_add_u32 m0, s100, 0x5000
	v_mfma_f32_16x16x32_bf16 v[160:163], v[132:135], v[18:21], v[160:163]
	global_load_lds_dwordx4 v[174:175], off
	v_mfma_f32_16x16x32_bf16 v[82:85], v[140:143], v[18:21], v[82:85]
	ds_read_b128 v[126:129], v128 offset:38912
	s_add_u32 m0, s100, 0x2000
	s_waitcnt lgkmcnt(5)
	v_mfma_f32_16x16x32_bf16 v[202:205], v[26:29], v[106:109], v[102:105]
	global_load_lds_dwordx4 v[188:189], off
	v_mfma_f32_16x16x32_bf16 v[78:81], v[30:33], v[106:109], v[78:81]
	ds_read_b128 v[206:209], v130 offset:49152
	s_add_u32 m0, s100, 0x6000
	v_mfma_f32_16x16x32_bf16 v[164:167], v[132:135], v[106:109], v[164:167]
	global_load_lds_dwordx4 v[176:177], off
	v_mfma_f32_16x16x32_bf16 v[70:73], v[140:143], v[106:109], v[70:73]
	ds_read_b128 v[210:213], v130 offset:51200
	s_add_u32 m0, s100, 0x3000
	s_waitcnt lgkmcnt(6)
	v_mfma_f32_16x16x32_bf16 v[214:217], v[26:29], v[122:125], v[98:101]
	global_load_lds_dwordx4 v[136:137], off
	v_mfma_f32_16x16x32_bf16 v[66:69], v[30:33], v[122:125], v[66:69]
	ds_read_b128 v[218:221], v130 offset:53248
	s_add_u32 m0, s100, 0x7000
	v_mfma_f32_16x16x32_bf16 v[110:113], v[132:135], v[122:125], v[110:113]
	global_load_lds_dwordx4 v[178:179], off
	v_mfma_f32_16x16x32_bf16 v[122:125], v[140:143], v[122:125], v[74:77]
	s_waitcnt lgkmcnt(2)
	v_mfma_f32_16x16x32_bf16 v[132:135], v[206:209], v[148:151], v[144:147]
	s_waitcnt lgkmcnt(0)
	v_mfma_f32_16x16x32_bf16 v[144:147], v[218:221], v[148:151], v[152:155]
	ds_read_b128 v[152:155], v130 offset:55296
	v_mfma_f32_16x16x32_bf16 v[140:143], v[210:213], v[148:151], v[94:97]
	s_waitcnt lgkmcnt(0)
	v_mfma_f32_16x16x32_bf16 v[148:151], v[152:155], v[148:151], v[90:93]
	v_mfma_f32_16x16x32_bf16 v[98:101], v[152:155], v[194:197], v[82:85]
	v_mfma_f32_16x16x32_bf16 v[90:93], v[210:213], v[198:201], v[78:81]
	v_mfma_f32_16x16x32_bf16 v[82:85], v[152:155], v[198:201], v[70:73]
	v_mfma_f32_16x16x32_bf16 v[78:81], v[206:209], v[126:129], v[214:217]
	v_mfma_f32_16x16x32_bf16 v[74:77], v[210:213], v[126:129], v[66:69]
	v_mfma_f32_16x16x32_bf16 v[66:69], v[218:221], v[126:129], v[110:113]
	v_mfma_f32_16x16x32_bf16 v[70:73], v[152:155], v[126:129], v[122:125]
	v_mfma_f32_16x16x32_bf16 v[156:159], v[206:209], v[194:197], v[156:159]
	v_mfma_f32_16x16x32_bf16 v[106:109], v[210:213], v[194:197], v[86:89]
	v_mfma_f32_16x16x32_bf16 v[102:105], v[218:221], v[194:197], v[160:163]
	v_mfma_f32_16x16x32_bf16 v[94:97], v[206:209], v[198:201], v[202:205]
	v_mfma_f32_16x16x32_bf16 v[86:89], v[218:221], v[198:201], v[164:167]
	s_setprio 0
	v_add_u32_e32 v110, s4, v116
	v_ashrrev_i32_e32 v111, 31, v110
	v_readlane_b32 s44, v253, 18
	v_lshlrev_b64 v[112:113], 12, v[110:111]
	v_or_b32_e32 v0, s5, v117
	v_readlane_b32 s58, v253, 32
	v_readlane_b32 s59, v253, 33
	v_lshlrev_b64 v[114:115], 2, v[0:1]
	v_lshl_add_u64 v[166:167], v[110:111], 3, s[0:1]
	v_lshl_add_u64 v[112:113], s[58:59], 0, v[112:113]
	v_lshl_add_u64 v[164:165], v[112:113], 0, v[114:115]
	s_barrier
	v_readlane_b32 s44, v253, 18
	v_readlane_b32 s45, v253, 19
	v_readlane_b32 s46, v253, 20
	v_readlane_b32 s47, v253, 21
	v_readlane_b32 s48, v253, 22
	v_readlane_b32 s49, v253, 23
	v_readlane_b32 s50, v253, 24
	v_readlane_b32 s51, v253, 25
	v_readlane_b32 s52, v253, 26
	v_readlane_b32 s53, v253, 27
	v_readlane_b32 s54, v253, 28
	v_readlane_b32 s55, v253, 29
	v_readlane_b32 s56, v253, 30
	v_readlane_b32 s57, v253, 31
	v_readlane_b32 s58, v253, 32
	v_readlane_b32 s59, v253, 33
	s_mov_b64 s[42:43], -1
	v_or_b32_e32 v0, s5, v117
	v_lshlrev_b32_e32 v0, 2, v0
	v_add_u32_e32 v110, s4, v116
	v_lshlrev_b32_e32 v50, 3, v110
	v_lshlrev_b32_e32 v110, 12, v110
	v_add_u32_e32 v110, v110, v0
	v_add_u32_e32 v111, s4, v118
	v_lshlrev_b32_e32 v54, 3, v111
	v_lshlrev_b32_e32 v111, 12, v111
	v_add_u32_e32 v111, v111, v0
	v_add_u32_e32 v112, s4, v119
	v_lshlrev_b32_e32 v58, 3, v112
	v_lshlrev_b32_e32 v112, 12, v112
	v_add_u32_e32 v112, v112, v0
	v_add_u32_e32 v113, s4, v120
	v_lshlrev_b32_e32 v62, 3, v113
	v_lshlrev_b32_e32 v113, 12, v113
	v_add_u32_e32 v113, v113, v0
	s_mov_b32 s14, 0x3fb504f3
	global_load_dwordx2 v[114:115], v50, s[0:1]
	global_load_dwordx2 v[122:123], v54, s[0:1]
	global_load_dwordx2 v[124:125], v58, s[0:1]
	global_load_dwordx2 v[126:127], v62, s[0:1]
	global_load_dwordx4 v[128:131], v0, s[34:35]
	global_load_dwordx4 v[226:229], v0, s[40:41]
	global_load_dwordx4 v[152:155], v0, s[34:35] offset:16
	global_load_dwordx4 v[230:233], v0, s[40:41] offset:16
	global_load_dwordx4 v[160:163], v0, s[34:35] offset:128
	global_load_dwordx4 v[234:237], v0, s[40:41] offset:128
	global_load_dwordx4 v[222:225], v0, s[34:35] offset:144
	global_load_dwordx4 v[238:241], v0, s[40:41] offset:144
	global_load_dwordx4 v[2:5], v110, s[58:59]
	global_load_dwordx4 v[18:21], v110, s[58:59] offset:16
	global_load_dwordx4 v[34:37], v110, s[58:59] offset:128
	global_load_dwordx4 v[50:53], v110, s[58:59] offset:144
	global_load_dwordx4 v[6:9], v111, s[58:59]
	global_load_dwordx4 v[22:25], v111, s[58:59] offset:16
	global_load_dwordx4 v[38:41], v111, s[58:59] offset:128
	global_load_dwordx4 v[54:57], v111, s[58:59] offset:144
	global_load_dwordx4 v[10:13], v112, s[58:59]
	global_load_dwordx4 v[26:29], v112, s[58:59] offset:16
	global_load_dwordx4 v[42:45], v112, s[58:59] offset:128
	global_load_dwordx4 v[58:61], v112, s[58:59] offset:144
	global_load_dwordx4 v[14:17], v113, s[58:59]
	global_load_dwordx4 v[30:33], v113, s[58:59] offset:16
	global_load_dwordx4 v[46:49], v113, s[58:59] offset:128
	global_load_dwordx4 v[62:65], v113, s[58:59] offset:144
	s_waitcnt vmcnt(15)
	v_pk_add_f32 v[2:3], v[2:3], v[114:115] op_sel_hi:[1,0] neg_lo:[0,1] neg_hi:[0,1]
	v_pk_add_f32 v[4:5], v[4:5], v[114:115] op_sel_hi:[1,0] neg_lo:[0,1] neg_hi:[0,1]
	v_pk_mul_f32 v[2:3], v[2:3], v[114:115] op_sel:[0,1]
	v_pk_mul_f32 v[4:5], v[4:5], v[114:115] op_sel:[0,1]
	v_pk_fma_f32 v[2:3], v[2:3], v[128:129], v[226:227]
	v_pk_fma_f32 v[4:5], v[4:5], v[130:131], v[228:229]
	v_pk_fma_f32 v[132:133], v[2:3], s[14:15], v[132:133] op_sel_hi:[1,0,1]
	v_pk_fma_f32 v[134:135], v[4:5], s[14:15], v[134:135] op_sel_hi:[1,0,1]
	global_store_dwordx4 v110, v[132:135], s[58:59]
	s_waitcnt vmcnt(15)
	v_pk_add_f32 v[18:19], v[18:19], v[114:115] op_sel_hi:[1,0] neg_lo:[0,1] neg_hi:[0,1]
	v_pk_add_f32 v[20:21], v[20:21], v[114:115] op_sel_hi:[1,0] neg_lo:[0,1] neg_hi:[0,1]
	v_pk_mul_f32 v[18:19], v[18:19], v[114:115] op_sel:[0,1]
	v_pk_mul_f32 v[20:21], v[20:21], v[114:115] op_sel:[0,1]
	v_pk_fma_f32 v[18:19], v[18:19], v[152:153], v[230:231]
	v_pk_fma_f32 v[20:21], v[20:21], v[154:155], v[232:233]
	v_pk_fma_f32 v[140:141], v[18:19], s[14:15], v[140:141] op_sel_hi:[1,0,1]
	v_pk_fma_f32 v[142:143], v[20:21], s[14:15], v[142:143] op_sel_hi:[1,0,1]
	global_store_dwordx4 v110, v[140:143], s[58:59] offset:16
	s_waitcnt vmcnt(15)
	v_pk_add_f32 v[34:35], v[34:35], v[114:115] op_sel_hi:[1,0] neg_lo:[0,1] neg_hi:[0,1]
	v_pk_add_f32 v[36:37], v[36:37], v[114:115] op_sel_hi:[1,0] neg_lo:[0,1] neg_hi:[0,1]
	v_pk_mul_f32 v[34:35], v[34:35], v[114:115] op_sel:[0,1]
	v_pk_mul_f32 v[36:37], v[36:37], v[114:115] op_sel:[0,1]
	v_pk_fma_f32 v[34:35], v[34:35], v[160:161], v[234:235]
	v_pk_fma_f32 v[36:37], v[36:37], v[162:163], v[236:237]
	v_pk_fma_f32 v[144:145], v[34:35], s[14:15], v[144:145] op_sel_hi:[1,0,1]
	v_pk_fma_f32 v[146:147], v[36:37], s[14:15], v[146:147] op_sel_hi:[1,0,1]
	global_store_dwordx4 v110, v[144:147], s[58:59] offset:128
	s_waitcnt vmcnt(15)
	v_pk_add_f32 v[50:51], v[50:51], v[114:115] op_sel_hi:[1,0] neg_lo:[0,1] neg_hi:[0,1]
	v_pk_add_f32 v[52:53], v[52:53], v[114:115] op_sel_hi:[1,0] neg_lo:[0,1] neg_hi:[0,1]
	v_pk_mul_f32 v[50:51], v[50:51], v[114:115] op_sel:[0,1]
	v_pk_mul_f32 v[52:53], v[52:53], v[114:115] op_sel:[0,1]
	v_pk_fma_f32 v[50:51], v[50:51], v[222:223], v[238:239]
	v_pk_fma_f32 v[52:53], v[52:53], v[224:225], v[240:241]
	v_pk_fma_f32 v[148:149], v[50:51], s[14:15], v[148:149] op_sel_hi:[1,0,1]
	v_pk_fma_f32 v[150:151], v[52:53], s[14:15], v[150:151] op_sel_hi:[1,0,1]
	global_store_dwordx4 v110, v[148:151], s[58:59] offset:144
	s_waitcnt vmcnt(15)
	v_pk_add_f32 v[6:7], v[6:7], v[122:123] op_sel_hi:[1,0] neg_lo:[0,1] neg_hi:[0,1]
	v_pk_add_f32 v[8:9], v[8:9], v[122:123] op_sel_hi:[1,0] neg_lo:[0,1] neg_hi:[0,1]
	v_pk_mul_f32 v[6:7], v[6:7], v[122:123] op_sel:[0,1]
	v_pk_mul_f32 v[8:9], v[8:9], v[122:123] op_sel:[0,1]
	v_pk_fma_f32 v[6:7], v[6:7], v[128:129], v[226:227]
	v_pk_fma_f32 v[8:9], v[8:9], v[130:131], v[228:229]
	v_pk_fma_f32 v[156:157], v[6:7], s[14:15], v[156:157] op_sel_hi:[1,0,1]
	v_pk_fma_f32 v[158:159], v[8:9], s[14:15], v[158:159] op_sel_hi:[1,0,1]
	global_store_dwordx4 v111, v[156:159], s[58:59]
	s_waitcnt vmcnt(15)
	v_pk_add_f32 v[22:23], v[22:23], v[122:123] op_sel_hi:[1,0] neg_lo:[0,1] neg_hi:[0,1]
	v_pk_add_f32 v[24:25], v[24:25], v[122:123] op_sel_hi:[1,0] neg_lo:[0,1] neg_hi:[0,1]
	v_pk_mul_f32 v[22:23], v[22:23], v[122:123] op_sel:[0,1]
	v_pk_mul_f32 v[24:25], v[24:25], v[122:123] op_sel:[0,1]
	v_pk_fma_f32 v[22:23], v[22:23], v[152:153], v[230:231]
	v_pk_fma_f32 v[24:25], v[24:25], v[154:155], v[232:233]
	v_pk_fma_f32 v[106:107], v[22:23], s[14:15], v[106:107] op_sel_hi:[1,0,1]
	v_pk_fma_f32 v[108:109], v[24:25], s[14:15], v[108:109] op_sel_hi:[1,0,1]
	global_store_dwordx4 v111, v[106:109], s[58:59] offset:16
	s_waitcnt vmcnt(15)
	v_pk_add_f32 v[38:39], v[38:39], v[122:123] op_sel_hi:[1,0] neg_lo:[0,1] neg_hi:[0,1]
	v_pk_add_f32 v[40:41], v[40:41], v[122:123] op_sel_hi:[1,0] neg_lo:[0,1] neg_hi:[0,1]
	v_pk_mul_f32 v[38:39], v[38:39], v[122:123] op_sel:[0,1]
	v_pk_mul_f32 v[40:41], v[40:41], v[122:123] op_sel:[0,1]
	v_pk_fma_f32 v[38:39], v[38:39], v[160:161], v[234:235]
	v_pk_fma_f32 v[40:41], v[40:41], v[162:163], v[236:237]
	v_pk_fma_f32 v[102:103], v[38:39], s[14:15], v[102:103] op_sel_hi:[1,0,1]
	v_pk_fma_f32 v[104:105], v[40:41], s[14:15], v[104:105] op_sel_hi:[1,0,1]
	global_store_dwordx4 v111, v[102:105], s[58:59] offset:128
	s_waitcnt vmcnt(15)
	v_pk_add_f32 v[54:55], v[54:55], v[122:123] op_sel_hi:[1,0] neg_lo:[0,1] neg_hi:[0,1]
	v_pk_add_f32 v[56:57], v[56:57], v[122:123] op_sel_hi:[1,0] neg_lo:[0,1] neg_hi:[0,1]
	v_pk_mul_f32 v[54:55], v[54:55], v[122:123] op_sel:[0,1]
	v_pk_mul_f32 v[56:57], v[56:57], v[122:123] op_sel:[0,1]
	v_pk_fma_f32 v[54:55], v[54:55], v[222:223], v[238:239]
	v_pk_fma_f32 v[56:57], v[56:57], v[224:225], v[240:241]
	v_pk_fma_f32 v[98:99], v[54:55], s[14:15], v[98:99] op_sel_hi:[1,0,1]
	v_pk_fma_f32 v[100:101], v[56:57], s[14:15], v[100:101] op_sel_hi:[1,0,1]
	global_store_dwordx4 v111, v[98:101], s[58:59] offset:144
	s_waitcnt vmcnt(15)
	v_pk_add_f32 v[10:11], v[10:11], v[124:125] op_sel_hi:[1,0] neg_lo:[0,1] neg_hi:[0,1]
	v_pk_add_f32 v[12:13], v[12:13], v[124:125] op_sel_hi:[1,0] neg_lo:[0,1] neg_hi:[0,1]
	v_pk_mul_f32 v[10:11], v[10:11], v[124:125] op_sel:[0,1]
	v_pk_mul_f32 v[12:13], v[12:13], v[124:125] op_sel:[0,1]
	v_pk_fma_f32 v[10:11], v[10:11], v[128:129], v[226:227]
	v_pk_fma_f32 v[12:13], v[12:13], v[130:131], v[228:229]
	v_pk_fma_f32 v[94:95], v[10:11], s[14:15], v[94:95] op_sel_hi:[1,0,1]
	v_pk_fma_f32 v[96:97], v[12:13], s[14:15], v[96:97] op_sel_hi:[1,0,1]
	global_store_dwordx4 v112, v[94:97], s[58:59]
	s_waitcnt vmcnt(15)
	v_pk_add_f32 v[26:27], v[26:27], v[124:125] op_sel_hi:[1,0] neg_lo:[0,1] neg_hi:[0,1]
	v_pk_add_f32 v[28:29], v[28:29], v[124:125] op_sel_hi:[1,0] neg_lo:[0,1] neg_hi:[0,1]
	v_pk_mul_f32 v[26:27], v[26:27], v[124:125] op_sel:[0,1]
	v_pk_mul_f32 v[28:29], v[28:29], v[124:125] op_sel:[0,1]
	v_pk_fma_f32 v[26:27], v[26:27], v[152:153], v[230:231]
	v_pk_fma_f32 v[28:29], v[28:29], v[154:155], v[232:233]
	v_pk_fma_f32 v[90:91], v[26:27], s[14:15], v[90:91] op_sel_hi:[1,0,1]
	v_pk_fma_f32 v[92:93], v[28:29], s[14:15], v[92:93] op_sel_hi:[1,0,1]
	global_store_dwordx4 v112, v[90:93], s[58:59] offset:16
	s_waitcnt vmcnt(15)
	v_pk_add_f32 v[42:43], v[42:43], v[124:125] op_sel_hi:[1,0] neg_lo:[0,1] neg_hi:[0,1]
	v_pk_add_f32 v[44:45], v[44:45], v[124:125] op_sel_hi:[1,0] neg_lo:[0,1] neg_hi:[0,1]
	v_pk_mul_f32 v[42:43], v[42:43], v[124:125] op_sel:[0,1]
	v_pk_mul_f32 v[44:45], v[44:45], v[124:125] op_sel:[0,1]
	v_pk_fma_f32 v[42:43], v[42:43], v[160:161], v[234:235]
	v_pk_fma_f32 v[44:45], v[44:45], v[162:163], v[236:237]
	v_pk_fma_f32 v[86:87], v[42:43], s[14:15], v[86:87] op_sel_hi:[1,0,1]
	v_pk_fma_f32 v[88:89], v[44:45], s[14:15], v[88:89] op_sel_hi:[1,0,1]
	global_store_dwordx4 v112, v[86:89], s[58:59] offset:128
	s_waitcnt vmcnt(15)
	v_pk_add_f32 v[58:59], v[58:59], v[124:125] op_sel_hi:[1,0] neg_lo:[0,1] neg_hi:[0,1]
	v_pk_add_f32 v[60:61], v[60:61], v[124:125] op_sel_hi:[1,0] neg_lo:[0,1] neg_hi:[0,1]
	v_pk_mul_f32 v[58:59], v[58:59], v[124:125] op_sel:[0,1]
	v_pk_mul_f32 v[60:61], v[60:61], v[124:125] op_sel:[0,1]
	v_pk_fma_f32 v[58:59], v[58:59], v[222:223], v[238:239]
	v_pk_fma_f32 v[60:61], v[60:61], v[224:225], v[240:241]
	v_pk_fma_f32 v[82:83], v[58:59], s[14:15], v[82:83] op_sel_hi:[1,0,1]
	v_pk_fma_f32 v[84:85], v[60:61], s[14:15], v[84:85] op_sel_hi:[1,0,1]
	global_store_dwordx4 v112, v[82:85], s[58:59] offset:144
	s_waitcnt vmcnt(15)
	v_pk_add_f32 v[14:15], v[14:15], v[126:127] op_sel_hi:[1,0] neg_lo:[0,1] neg_hi:[0,1]
	v_pk_add_f32 v[16:17], v[16:17], v[126:127] op_sel_hi:[1,0] neg_lo:[0,1] neg_hi:[0,1]
	v_pk_mul_f32 v[14:15], v[14:15], v[126:127] op_sel:[0,1]
	v_pk_mul_f32 v[16:17], v[16:17], v[126:127] op_sel:[0,1]
	v_pk_fma_f32 v[14:15], v[14:15], v[128:129], v[226:227]
	v_pk_fma_f32 v[16:17], v[16:17], v[130:131], v[228:229]
	v_pk_fma_f32 v[78:79], v[14:15], s[14:15], v[78:79] op_sel_hi:[1,0,1]
	v_pk_fma_f32 v[80:81], v[16:17], s[14:15], v[80:81] op_sel_hi:[1,0,1]
	global_store_dwordx4 v113, v[78:81], s[58:59]
	s_waitcnt vmcnt(15)
	v_pk_add_f32 v[30:31], v[30:31], v[126:127] op_sel_hi:[1,0] neg_lo:[0,1] neg_hi:[0,1]
	v_pk_add_f32 v[32:33], v[32:33], v[126:127] op_sel_hi:[1,0] neg_lo:[0,1] neg_hi:[0,1]
	v_pk_mul_f32 v[30:31], v[30:31], v[126:127] op_sel:[0,1]
	v_pk_mul_f32 v[32:33], v[32:33], v[126:127] op_sel:[0,1]
	v_pk_fma_f32 v[30:31], v[30:31], v[152:153], v[230:231]
	v_pk_fma_f32 v[32:33], v[32:33], v[154:155], v[232:233]
	v_pk_fma_f32 v[74:75], v[30:31], s[14:15], v[74:75] op_sel_hi:[1,0,1]
	v_pk_fma_f32 v[76:77], v[32:33], s[14:15], v[76:77] op_sel_hi:[1,0,1]
	global_store_dwordx4 v113, v[74:77], s[58:59] offset:16
	s_waitcnt vmcnt(15)
	v_pk_add_f32 v[46:47], v[46:47], v[126:127] op_sel_hi:[1,0] neg_lo:[0,1] neg_hi:[0,1]
	v_pk_add_f32 v[48:49], v[48:49], v[126:127] op_sel_hi:[1,0] neg_lo:[0,1] neg_hi:[0,1]
	v_pk_mul_f32 v[46:47], v[46:47], v[126:127] op_sel:[0,1]
	v_pk_mul_f32 v[48:49], v[48:49], v[126:127] op_sel:[0,1]
	v_pk_fma_f32 v[46:47], v[46:47], v[160:161], v[234:235]
	v_pk_fma_f32 v[48:49], v[48:49], v[162:163], v[236:237]
	v_pk_fma_f32 v[66:67], v[46:47], s[14:15], v[66:67] op_sel_hi:[1,0,1]
	v_pk_fma_f32 v[68:69], v[48:49], s[14:15], v[68:69] op_sel_hi:[1,0,1]
	global_store_dwordx4 v113, v[66:69], s[58:59] offset:128
	s_waitcnt vmcnt(15)
	v_pk_add_f32 v[62:63], v[62:63], v[126:127] op_sel_hi:[1,0] neg_lo:[0,1] neg_hi:[0,1]
	v_pk_add_f32 v[64:65], v[64:65], v[126:127] op_sel_hi:[1,0] neg_lo:[0,1] neg_hi:[0,1]
	v_pk_mul_f32 v[62:63], v[62:63], v[126:127] op_sel:[0,1]
	v_pk_mul_f32 v[64:65], v[64:65], v[126:127] op_sel:[0,1]
	v_pk_fma_f32 v[62:63], v[62:63], v[222:223], v[238:239]
	v_pk_fma_f32 v[64:65], v[64:65], v[224:225], v[240:241]
	v_pk_fma_f32 v[70:71], v[62:63], s[14:15], v[70:71] op_sel_hi:[1,0,1]
	v_pk_fma_f32 v[72:73], v[64:65], s[14:15], v[72:73] op_sel_hi:[1,0,1]
	global_store_dwordx4 v113, v[70:73], s[58:59] offset:144
	s_cmp_lg_u32 s101, 0
	s_cbranch_scc1 .LBB0_126
	v_mov_b32_e32 v0, v169
	v_mov_b32_e32 v67, v169
	s_movk_i32 s4, 0xb00
	v_lshrrev_b32_e32 v66, 3, v0
	v_lshrrev_b32_e32 v69, 3, v67
	v_add_u32_e32 v66, s9, v66
	v_add_u32_e32 v69, s10, v69
	v_lshlrev_b32_e32 v0, 3, v0
	v_mul_lo_u32 v66, v66, s4
	v_lshlrev_b32_e32 v67, 3, v67
	v_mul_lo_u32 v69, v69, s4
	v_and_or_b32 v0, v0, 56, v66
	v_and_or_b32 v72, v67, 56, v69
	v_add_u32_e32 v66, 0x16000, v0
	v_add_u32_e32 v68, 0x2c000, v0
	v_add_u32_e32 v70, 0x42000, v0
	v_add_u32_e32 v74, 0x16000, v72
	v_add_u32_e32 v76, 0x2c000, v72
	v_add_u32_e32 v78, 0x42000, v72
	s_mov_b64 s[42:43], 0
	s_branch .LBB0_126

.LBB0_157:
	s_setprio 1
	s_add_u32 s98, s38, s36
	s_addc_u32 s99, s39, 0
	s_add_u32 s98, s98, 0x80
	s_addc_u32 s99, s99, 0
	v_add_u32_e32 v122, v119, v118
	v_add_u32_e32 v124, v119, v120
	v_add_u32_e32 v123, v121, v120
	ds_read_b128 v[126:129], v122 offset:16384
	ds_read_b128 v[130:133], v124
	ds_read_b128 v[144:147], v122 offset:18432
	ds_read_b128 v[158:161], v122 offset:20480
	ds_read_b128 v[162:165], v122 offset:22528
	ds_read_b128 v[134:137], v124 offset:2048
	ds_read_b128 v[140:143], v124 offset:4096
	ds_read_b128 v[148:151], v124 offset:6144
	s_add_u32 m0, s100, 0x8000
	s_waitcnt lgkmcnt(6)
	v_mfma_f32_16x16x32_bf16 v[34:37], v[126:129], v[130:133], v[34:37]
	global_load_lds_dwordx4 v194, s[98:99]
	s_waitcnt lgkmcnt(5)
	v_mfma_f32_16x16x32_bf16 v[94:97], v[144:147], v[130:133], v[94:97]
	ds_read_b128 v[198:201], v123
	s_add_u32 m0, s100, 0xc000
	s_waitcnt lgkmcnt(5)
	v_mfma_f32_16x16x32_bf16 v[38:41], v[158:161], v[130:133], v[38:41]
	global_load_lds_dwordx4 v195, s[98:99]
	s_waitcnt lgkmcnt(4)
	v_mfma_f32_16x16x32_bf16 v[90:93], v[162:165], v[130:133], v[90:93]
	ds_read_b128 v[206:209], v123 offset:2048
	s_add_u32 m0, s100, 0x9000
	s_waitcnt lgkmcnt(4)
	v_mfma_f32_16x16x32_bf16 v[42:45], v[126:129], v[134:137], v[42:45]
	global_load_lds_dwordx4 v196, s[98:99]
	v_mfma_f32_16x16x32_bf16 v[86:89], v[144:147], v[134:137], v[86:89]
	ds_read_b128 v[214:217], v123 offset:4096
	s_add_u32 m0, s100, 0xd000
	v_mfma_f32_16x16x32_bf16 v[46:49], v[158:161], v[134:137], v[46:49]
	global_load_lds_dwordx4 v197, s[98:99]
	v_mfma_f32_16x16x32_bf16 v[82:85], v[162:165], v[134:137], v[82:85]
	v_add_u32_e32 v130, v121, v118
	ds_read_b128 v[132:135], v123 offset:6144
	s_add_u32 m0, s100, 0xa000
	s_waitcnt lgkmcnt(5)
	v_mfma_f32_16x16x32_bf16 v[50:53], v[126:129], v[140:143], v[50:53]
	global_load_lds_dwordx4 v202, s[98:99]
	v_mfma_f32_16x16x32_bf16 v[78:81], v[144:147], v[140:143], v[78:81]
	ds_read_b128 v[226:229], v130 offset:16384
	s_add_u32 m0, s100, 0xe000
	v_mfma_f32_16x16x32_bf16 v[54:57], v[158:161], v[140:143], v[54:57]
	global_load_lds_dwordx4 v203, s[98:99]
	v_mfma_f32_16x16x32_bf16 v[70:73], v[162:165], v[140:143], v[70:73]
	ds_read_b128 v[140:143], v130 offset:18432
	s_add_u32 m0, s100, 0xb000
	s_waitcnt lgkmcnt(6)
	v_mfma_f32_16x16x32_bf16 v[58:61], v[126:129], v[148:151], v[58:61]
	global_load_lds_dwordx4 v204, s[98:99]
	v_mfma_f32_16x16x32_bf16 v[66:69], v[144:147], v[148:151], v[66:69]
	ds_read_b128 v[144:147], v130 offset:20480
	s_add_u32 m0, s100, 0xf000
	v_mfma_f32_16x16x32_bf16 v[62:65], v[158:161], v[148:151], v[62:65]
	global_load_lds_dwordx4 v205, s[98:99]
	v_mfma_f32_16x16x32_bf16 v[74:77], v[162:165], v[148:151], v[74:77]
	ds_read_b128 v[148:151], v130 offset:22528
	s_waitcnt lgkmcnt(3)
	v_mfma_f32_16x16x32_bf16 v[34:37], v[226:229], v[198:201], v[34:37]
	s_waitcnt lgkmcnt(2)
	v_mfma_f32_16x16x32_bf16 v[94:97], v[140:143], v[198:201], v[94:97]
	s_waitcnt lgkmcnt(1)
	v_mfma_f32_16x16x32_bf16 v[38:41], v[144:147], v[198:201], v[38:41]
	s_waitcnt lgkmcnt(0)
	v_mfma_f32_16x16x32_bf16 v[90:93], v[148:151], v[198:201], v[90:93]
	v_mfma_f32_16x16x32_bf16 v[42:45], v[226:229], v[206:209], v[42:45]
	v_mfma_f32_16x16x32_bf16 v[86:89], v[140:143], v[206:209], v[86:89]
	v_mfma_f32_16x16x32_bf16 v[46:49], v[144:147], v[206:209], v[46:49]
	v_mfma_f32_16x16x32_bf16 v[82:85], v[148:151], v[206:209], v[82:85]
	v_mfma_f32_16x16x32_bf16 v[50:53], v[226:229], v[214:217], v[50:53]
	v_mfma_f32_16x16x32_bf16 v[78:81], v[140:143], v[214:217], v[78:81]
	v_mfma_f32_16x16x32_bf16 v[54:57], v[144:147], v[214:217], v[54:57]
	v_mfma_f32_16x16x32_bf16 v[70:73], v[148:151], v[214:217], v[70:73]
	v_mfma_f32_16x16x32_bf16 v[58:61], v[226:229], v[132:135], v[58:61]
	v_mfma_f32_16x16x32_bf16 v[66:69], v[140:143], v[132:135], v[66:69]
	v_mfma_f32_16x16x32_bf16 v[62:65], v[144:147], v[132:135], v[62:65]
	v_mfma_f32_16x16x32_bf16 v[74:77], v[148:151], v[132:135], v[74:77]
	s_waitcnt vmcnt(0)
	s_setprio 0
	s_waitcnt lgkmcnt(0)
	s_barrier
	s_setprio 1
	s_add_u32 s98, s98, 0x80
	s_addc_u32 s99, s99, 0
	ds_read_b128 v[26:29], v122 offset:49152
	ds_read_b128 v[10:13], v124 offset:32768
	ds_read_b128 v[30:33], v122 offset:51200
	ds_read_b128 v[144:147], v122 offset:53248
	ds_read_b128 v[148:151], v122 offset:55296
	ds_read_b128 v[18:21], v124 offset:34816
	ds_read_b128 v[132:135], v124 offset:36864
	ds_read_b128 v[140:143], v124 offset:38912
	s_add_u32 m0, s100, 0x0
	s_waitcnt lgkmcnt(6)
	v_mfma_f32_16x16x32_bf16 v[34:37], v[26:29], v[10:13], v[34:37]
	global_load_lds_dwordx4 v194, s[98:99]
	s_waitcnt lgkmcnt(5)
	v_mfma_f32_16x16x32_bf16 v[94:97], v[30:33], v[10:13], v[94:97]
	ds_read_b128 v[162:165], v123 offset:32768
	s_add_u32 m0, s100, 0x4000
	s_waitcnt lgkmcnt(5)
	v_mfma_f32_16x16x32_bf16 v[38:41], v[144:147], v[10:13], v[38:41]
	global_load_lds_dwordx4 v195, s[98:99]
	s_waitcnt lgkmcnt(4)
	v_mfma_f32_16x16x32_bf16 v[90:93], v[148:151], v[10:13], v[90:93]
	ds_read_b128 v[198:201], v123 offset:34816
	s_add_u32 m0, s100, 0x1000
	s_waitcnt lgkmcnt(4)
	v_mfma_f32_16x16x32_bf16 v[42:45], v[26:29], v[18:21], v[42:45]
	global_load_lds_dwordx4 v196, s[98:99]
	v_mfma_f32_16x16x32_bf16 v[86:89], v[30:33], v[18:21], v[86:89]
	ds_read_b128 v[206:209], v123 offset:36864
	s_add_u32 m0, s100, 0x5000
	v_mfma_f32_16x16x32_bf16 v[46:49], v[144:147], v[18:21], v[46:49]
	global_load_lds_dwordx4 v197, s[98:99]
	v_mfma_f32_16x16x32_bf16 v[82:85], v[148:151], v[18:21], v[82:85]
	ds_read_b128 v[214:217], v123 offset:38912
	s_add_u32 m0, s100, 0x2000
	s_waitcnt lgkmcnt(5)
	v_mfma_f32_16x16x32_bf16 v[50:53], v[26:29], v[132:135], v[50:53]
	global_load_lds_dwordx4 v202, s[98:99]
	v_mfma_f32_16x16x32_bf16 v[78:81], v[30:33], v[132:135], v[78:81]
	ds_read_b128 v[226:229], v130 offset:49152
	s_add_u32 m0, s100, 0x6000
	v_mfma_f32_16x16x32_bf16 v[54:57], v[144:147], v[132:135], v[54:57]
	global_load_lds_dwordx4 v203, s[98:99]
	v_mfma_f32_16x16x32_bf16 v[70:73], v[148:151], v[132:135], v[70:73]
	ds_read_b128 v[132:135], v130 offset:51200
	s_add_u32 m0, s100, 0x3000
	s_waitcnt lgkmcnt(6)
	v_mfma_f32_16x16x32_bf16 v[58:61], v[26:29], v[140:143], v[58:61]
	global_load_lds_dwordx4 v204, s[98:99]
	v_mfma_f32_16x16x32_bf16 v[66:69], v[30:33], v[140:143], v[66:69]
	ds_read_b128 v[234:237], v130 offset:53248
	s_add_u32 m0, s100, 0x7000
	v_mfma_f32_16x16x32_bf16 v[62:65], v[144:147], v[140:143], v[62:65]
	global_load_lds_dwordx4 v205, s[98:99]
	v_mfma_f32_16x16x32_bf16 v[74:77], v[148:151], v[140:143], v[74:77]
	ds_read_b128 v[140:143], v130 offset:55296
	s_waitcnt lgkmcnt(3)
	v_mfma_f32_16x16x32_bf16 v[34:37], v[226:229], v[162:165], v[34:37]
	s_waitcnt lgkmcnt(2)
	v_mfma_f32_16x16x32_bf16 v[94:97], v[132:135], v[162:165], v[94:97]
	s_waitcnt lgkmcnt(1)
	v_mfma_f32_16x16x32_bf16 v[38:41], v[234:237], v[162:165], v[38:41]
	s_waitcnt lgkmcnt(0)
	v_mfma_f32_16x16x32_bf16 v[90:93], v[140:143], v[162:165], v[90:93]
	v_mfma_f32_16x16x32_bf16 v[42:45], v[226:229], v[198:201], v[42:45]
	v_mfma_f32_16x16x32_bf16 v[86:89], v[132:135], v[198:201], v[86:89]
	v_mfma_f32_16x16x32_bf16 v[46:49], v[234:237], v[198:201], v[46:49]
	v_mfma_f32_16x16x32_bf16 v[82:85], v[140:143], v[198:201], v[82:85]
	v_mfma_f32_16x16x32_bf16 v[50:53], v[226:229], v[206:209], v[50:53]
	v_mfma_f32_16x16x32_bf16 v[78:81], v[132:135], v[206:209], v[78:81]
	v_mfma_f32_16x16x32_bf16 v[54:57], v[234:237], v[206:209], v[54:57]
	v_mfma_f32_16x16x32_bf16 v[70:73], v[140:143], v[206:209], v[70:73]
	v_mfma_f32_16x16x32_bf16 v[58:61], v[226:229], v[214:217], v[58:61]
	v_mfma_f32_16x16x32_bf16 v[66:69], v[132:135], v[214:217], v[66:69]
	v_mfma_f32_16x16x32_bf16 v[62:65], v[234:237], v[214:217], v[62:65]
	v_mfma_f32_16x16x32_bf16 v[74:77], v[140:143], v[214:217], v[74:77]
	s_waitcnt vmcnt(0)
	s_setprio 0
	s_add_i32 s5, s5, 2
	s_add_u32 s38, s38, 0x100
	s_addc_u32 s39, s39, 0
	s_cmp_lt_u32 s5, 12
	s_waitcnt lgkmcnt(0)
	s_barrier
	s_cbranch_scc1 .LBB0_157
	v_mov_b32_e32 v2, v194
	v_mov_b32_e32 v3, v195
	v_mov_b32_e32 v4, v196
	v_mov_b32_e32 v5, v197
	v_mov_b32_e32 v6, v202
	v_mov_b32_e32 v7, v203
	v_mov_b32_e32 v8, v204
	v_mov_b32_e32 v9, v205
	s_add_u32 s98, s38, s36
	s_addc_u32 s99, s39, 0
	s_add_u32 s98, s98, 0x80
	s_addc_u32 s99, s99, 0
	s_add_i32 s5, s11, s2
	s_cmpk_lt_u32 s5, 0x100
	s_cselect_b64 s[44:45], -1, 0
	s_and_b64 s[8:9], s[44:45], exec
	s_cselect_b32 s9, s5, s11
	s_lshr_b32 s8, s9, 3
	s_and_b32 s8, s8, 0x1fffff8
	s_add_i32 s8, s8, s21
	s_and_b32 s11, s9, 7
	v_mov_b32_e32 v0, v169
	s_or_b32 s8, s8, s11
	s_lshl_b32 s8, s8, 7
	v_lshrrev_b32_e32 v98, 3, v0
	v_lshlrev_b32_e32 v0, 3, v0
	v_add_u32_e32 v98, s8, v98
	v_and_b32_e32 v0, 56, v0
	v_lshl_or_b32 v0, v98, 10, v0
	v_mov_b32_e32 v98, v169
	s_lshl_b32 s9, s9, 4
	s_and_b32 s9, s9, 0x380
	v_lshrrev_b32_e32 v99, 3, v98
	v_lshlrev_b32_e32 v98, 3, v98
	v_add_u32_e32 v99, s9, v99
	v_and_b32_e32 v98, 56, v98
	v_add_u32_e32 v114, 0x8000, v0
	v_add_u32_e32 v136, 0x10000, v0
	v_lshl_or_b32 v162, v99, 10, v98
	v_add_u32_e32 v166, 0x18000, v0
	v_add_u32_e32 v174, 0x8000, v162
	v_add_u32_e32 v176, 0x10000, v162
	v_add_u32_e32 v178, 0x18000, v162
	s_setprio 1
	ds_read_b128 v[98:101], v122 offset:16384
	ds_read_b128 v[102:105], v124
	ds_read_b128 v[110:113], v122 offset:18432
	ds_read_b128 v[132:135], v122 offset:20480
	ds_read_b128 v[140:143], v122 offset:22528
	ds_read_b128 v[106:109], v124 offset:2048
	ds_read_b128 v[118:121], v124 offset:4096
	ds_read_b128 v[126:129], v124 offset:6144
	v_lshrrev_b32_e32 v14, 3, v169
	v_and_b32_e32 v15, 3, v14
	v_bfe_u32 v16, v14, 4, 1
	v_lshl_or_b32 v15, v16, 2, v15
	v_bfe_u32 v16, v14, 2, 1
	v_lshl_or_b32 v15, v16, 3, v15
	v_bfe_u32 v16, v14, 3, 1
	v_lshl_or_b32 v15, v16, 4, v15
	v_sub_u32_e32 v15, v15, v14
	v_mul_i32_i24_e32 v15, 0x400, v15
	v_and_b32_e32 v14, 7, v14
	v_lshlrev_b32_e32 v14, 3, v14
	v_xor_b32_e32 v0, v0, v14
	v_add_u32_e32 v162, v162, v15
	v_xor_b32_e32 v162, v162, v14
	v_xor_b32_e32 v114, v114, v14
	v_add_u32_e32 v174, v174, v15
	v_xor_b32_e32 v174, v174, v14
	v_xor_b32_e32 v136, v136, v14
	v_add_u32_e32 v176, v176, v15
	v_xor_b32_e32 v176, v176, v14
	v_xor_b32_e32 v166, v166, v14
	v_add_u32_e32 v178, v178, v15
	v_xor_b32_e32 v178, v178, v14
	v_readlane_b32 s14, v254, 45
	v_readlane_b32 s15, v254, 46
	v_mov_b32_e32 v163, v1
	v_mov_b32_e32 v115, v1
	v_mov_b32_e32 v175, v1
	v_mov_b32_e32 v137, v1
	v_mov_b32_e32 v177, v1
	v_mov_b32_e32 v167, v1
	v_mov_b32_e32 v179, v1
	v_lshl_add_u64 v[180:181], v[0:1], 1, s[14:15]
	v_lshl_add_u64 v[186:187], v[162:163], 1, s[34:35]
	v_lshl_add_u64 v[188:189], v[114:115], 1, s[14:15]
	v_lshl_add_u64 v[174:175], v[174:175], 1, s[34:35]
	v_lshl_add_u64 v[136:137], v[136:137], 1, s[14:15]
	v_lshl_add_u64 v[176:177], v[176:177], 1, s[34:35]
	v_lshl_add_u64 v[166:167], v[166:167], 1, s[14:15]
	v_lshl_add_u64 v[178:179], v[178:179], 1, s[34:35]
	s_add_u32 m0, s100, 0x8000
	s_waitcnt lgkmcnt(6)
	v_mfma_f32_16x16x32_bf16 v[144:147], v[98:101], v[102:105], v[34:37]
	global_load_lds_dwordx4 v2, s[98:99]
	s_waitcnt lgkmcnt(5)
	v_mfma_f32_16x16x32_bf16 v[94:97], v[110:113], v[102:105], v[94:97]
	ds_read_b128 v[148:151], v123
	s_add_u32 m0, s100, 0xc000
	s_waitcnt lgkmcnt(5)
	v_mfma_f32_16x16x32_bf16 v[158:161], v[132:135], v[102:105], v[38:41]
	global_load_lds_dwordx4 v3, s[98:99]
	s_waitcnt lgkmcnt(4)
	v_mfma_f32_16x16x32_bf16 v[90:93], v[140:143], v[102:105], v[90:93]
	ds_read_b128 v[102:105], v123 offset:2048
	s_add_u32 m0, s100, 0x9000
	s_waitcnt lgkmcnt(4)
	v_mfma_f32_16x16x32_bf16 v[162:165], v[98:101], v[106:109], v[42:45]
	global_load_lds_dwordx4 v4, s[98:99]
	v_mfma_f32_16x16x32_bf16 v[86:89], v[110:113], v[106:109], v[86:89]
	ds_read_b128 v[194:197], v123 offset:4096
	s_add_u32 m0, s100, 0xd000
	v_mfma_f32_16x16x32_bf16 v[198:201], v[132:135], v[106:109], v[46:49]
	global_load_lds_dwordx4 v5, s[98:99]
	v_mfma_f32_16x16x32_bf16 v[82:85], v[140:143], v[106:109], v[82:85]
	ds_read_b128 v[106:109], v123 offset:6144
	s_add_u32 m0, s100, 0xa000
	s_waitcnt lgkmcnt(5)
	v_mfma_f32_16x16x32_bf16 v[202:205], v[98:101], v[118:121], v[50:53]
	global_load_lds_dwordx4 v6, s[98:99]
	v_mfma_f32_16x16x32_bf16 v[78:81], v[110:113], v[118:121], v[78:81]
	ds_read_b128 v[206:209], v130 offset:16384
	s_add_u32 m0, s100, 0xe000
	v_mfma_f32_16x16x32_bf16 v[210:213], v[132:135], v[118:121], v[54:57]
	global_load_lds_dwordx4 v7, s[98:99]
	v_mfma_f32_16x16x32_bf16 v[70:73], v[140:143], v[118:121], v[70:73]
	ds_read_b128 v[118:121], v130 offset:18432
	s_add_u32 m0, s100, 0xb000
	s_waitcnt lgkmcnt(6)
	v_mfma_f32_16x16x32_bf16 v[98:101], v[98:101], v[126:129], v[58:61]
	global_load_lds_dwordx4 v8, s[98:99]
	v_mfma_f32_16x16x32_bf16 v[66:69], v[110:113], v[126:129], v[66:69]
	ds_read_b128 v[110:113], v130 offset:20480
	s_add_u32 m0, s100, 0xf000
	v_mfma_f32_16x16x32_bf16 v[132:135], v[132:135], v[126:129], v[62:65]
	global_load_lds_dwordx4 v9, s[98:99]
	v_mfma_f32_16x16x32_bf16 v[74:77], v[140:143], v[126:129], v[74:77]
	ds_read_b128 v[126:129], v130 offset:22528
	s_waitcnt lgkmcnt(3)
	v_mfma_f32_16x16x32_bf16 v[140:143], v[206:209], v[148:151], v[144:147]
	s_waitcnt lgkmcnt(2)
	v_mfma_f32_16x16x32_bf16 v[94:97], v[118:121], v[148:151], v[94:97]
	s_waitcnt lgkmcnt(1)
	v_mfma_f32_16x16x32_bf16 v[144:147], v[110:113], v[148:151], v[158:161]
	s_waitcnt lgkmcnt(0)
	v_mfma_f32_16x16x32_bf16 v[90:93], v[126:129], v[148:151], v[90:93]
	v_mfma_f32_16x16x32_bf16 v[148:151], v[206:209], v[102:105], v[162:165]
	v_mfma_f32_16x16x32_bf16 v[86:89], v[118:121], v[102:105], v[86:89]
	v_mfma_f32_16x16x32_bf16 v[158:161], v[110:113], v[102:105], v[198:201]
	v_mfma_f32_16x16x32_bf16 v[82:85], v[126:129], v[102:105], v[82:85]
	v_mfma_f32_16x16x32_bf16 v[102:105], v[206:209], v[194:197], v[202:205]
	v_mfma_f32_16x16x32_bf16 v[78:81], v[118:121], v[194:197], v[78:81]
	v_mfma_f32_16x16x32_bf16 v[162:165], v[110:113], v[194:197], v[210:213]
	v_mfma_f32_16x16x32_bf16 v[70:73], v[126:129], v[194:197], v[70:73]
	v_mfma_f32_16x16x32_bf16 v[98:101], v[206:209], v[106:109], v[98:101]
	v_mfma_f32_16x16x32_bf16 v[66:69], v[118:121], v[106:109], v[66:69]
	v_mfma_f32_16x16x32_bf16 v[110:113], v[110:113], v[106:109], v[132:135]
	v_mfma_f32_16x16x32_bf16 v[74:77], v[126:129], v[106:109], v[74:77]
	s_waitcnt vmcnt(0)
	s_setprio 0
	s_waitcnt lgkmcnt(0)
	s_barrier
	s_setprio 1
	ds_read_b128 v[26:29], v122 offset:49152
	ds_read_b128 v[10:13], v124 offset:32768
	ds_read_b128 v[18:21], v124 offset:34816
	ds_read_b128 v[30:33], v122 offset:51200
	ds_read_b128 v[106:109], v124 offset:36864
	ds_read_b128 v[114:117], v124 offset:38912
	ds_read_b128 v[118:121], v122 offset:53248
	ds_read_b128 v[124:127], v122 offset:55296
	s_add_u32 m0, s100, 0x0
	s_waitcnt lgkmcnt(6)
	v_mfma_f32_16x16x32_bf16 v[132:135], v[26:29], v[10:13], v[140:143]
	global_load_lds_dwordx4 v[180:181], off
	s_waitcnt lgkmcnt(4)
	v_mfma_f32_16x16x32_bf16 v[94:97], v[30:33], v[10:13], v[94:97]
	ds_read_b128 v[140:143], v123 offset:32768
	s_add_u32 m0, s100, 0x4000
	s_waitcnt lgkmcnt(2)
	v_mfma_f32_16x16x32_bf16 v[144:147], v[118:121], v[10:13], v[144:147]
	global_load_lds_dwordx4 v[186:187], off
	s_waitcnt lgkmcnt(1)
	v_mfma_f32_16x16x32_bf16 v[90:93], v[124:127], v[10:13], v[90:93]
	ds_read_b128 v[194:197], v123 offset:34816
	s_add_u32 m0, s100, 0x1000
	v_mfma_f32_16x16x32_bf16 v[148:151], v[26:29], v[18:21], v[148:151]
	global_load_lds_dwordx4 v[188:189], off
	v_mfma_f32_16x16x32_bf16 v[86:89], v[30:33], v[18:21], v[86:89]
	ds_read_b128 v[198:201], v123 offset:36864
	s_add_u32 m0, s100, 0x5000
	v_mfma_f32_16x16x32_bf16 v[158:161], v[118:121], v[18:21], v[158:161]
	global_load_lds_dwordx4 v[174:175], off
	v_mfma_f32_16x16x32_bf16 v[82:85], v[124:127], v[18:21], v[82:85]
	ds_read_b128 v[202:205], v123 offset:38912
	s_add_u32 m0, s100, 0x2000
	v_mfma_f32_16x16x32_bf16 v[206:209], v[26:29], v[106:109], v[102:105]
	global_load_lds_dwordx4 v[136:137], off
	v_mfma_f32_16x16x32_bf16 v[78:81], v[30:33], v[106:109], v[78:81]
	ds_read_b128 v[210:213], v130 offset:49152
	s_add_u32 m0, s100, 0x6000
	v_mfma_f32_16x16x32_bf16 v[162:165], v[118:121], v[106:109], v[162:165]
	global_load_lds_dwordx4 v[176:177], off
	v_mfma_f32_16x16x32_bf16 v[70:73], v[124:127], v[106:109], v[70:73]
	ds_read_b128 v[214:217], v130 offset:51200
	s_add_u32 m0, s100, 0x3000
	v_mfma_f32_16x16x32_bf16 v[218:221], v[26:29], v[114:117], v[98:101]
	global_load_lds_dwordx4 v[166:167], off
	v_mfma_f32_16x16x32_bf16 v[66:69], v[30:33], v[114:117], v[66:69]
	ds_read_b128 v[222:225], v130 offset:53248
	s_add_u32 m0, s100, 0x7000
	v_mfma_f32_16x16x32_bf16 v[226:229], v[118:121], v[114:117], v[110:113]
	global_load_lds_dwordx4 v[178:179], off
	v_mfma_f32_16x16x32_bf16 v[230:233], v[124:127], v[114:117], v[74:77]
	s_waitcnt lgkmcnt(2)
	v_mfma_f32_16x16x32_bf16 v[126:129], v[210:213], v[140:143], v[132:135]
	ds_read_b128 v[130:133], v130 offset:55296
	s_waitcnt lgkmcnt(2)
	v_mfma_f32_16x16x32_bf16 v[122:125], v[214:217], v[140:143], v[94:97]
	s_waitcnt lgkmcnt(1)
	v_mfma_f32_16x16x32_bf16 v[118:121], v[222:225], v[140:143], v[144:147]
	s_waitcnt lgkmcnt(0)
	v_mfma_f32_16x16x32_bf16 v[114:117], v[130:133], v[140:143], v[90:93]
	v_mfma_f32_16x16x32_bf16 v[110:113], v[210:213], v[194:197], v[148:151]
	v_mfma_f32_16x16x32_bf16 v[106:109], v[214:217], v[194:197], v[86:89]
	v_mfma_f32_16x16x32_bf16 v[102:105], v[222:225], v[194:197], v[158:161]
	v_mfma_f32_16x16x32_bf16 v[98:101], v[130:133], v[194:197], v[82:85]
	v_mfma_f32_16x16x32_bf16 v[94:97], v[210:213], v[198:201], v[206:209]
	v_mfma_f32_16x16x32_bf16 v[90:93], v[214:217], v[198:201], v[78:81]
	v_mfma_f32_16x16x32_bf16 v[86:89], v[222:225], v[198:201], v[162:165]
	v_mfma_f32_16x16x32_bf16 v[82:85], v[130:133], v[198:201], v[70:73]
	v_mfma_f32_16x16x32_bf16 v[78:81], v[210:213], v[202:205], v[218:221]
	v_mfma_f32_16x16x32_bf16 v[74:77], v[214:217], v[202:205], v[66:69]
	v_mfma_f32_16x16x32_bf16 v[70:73], v[222:225], v[202:205], v[226:229]
	v_mfma_f32_16x16x32_bf16 v[66:69], v[130:133], v[202:205], v[230:233]
	s_setprio 0
	v_add_u32_e32 v134, s4, v152
	v_ashrrev_i32_e32 v135, 31, v134
	v_lshlrev_b64 v[136:137], 12, v[134:135]
	v_or_b32_e32 v140, s10, v153
	v_mov_b32_e32 v141, v1
	v_cndmask_b32_e64 v0, 0, 1, s[42:43]
	v_lshl_add_u64 v[130:131], s[40:41], 0, v[136:137]
	v_cmp_ne_u32_e64 s[38:39], 1, v0
	s_andn2_b64 vcc, exec, s[42:43]
	v_lshl_add_u64 v[146:147], v[140:141], 2, v[130:131]
	s_barrier
	v_readlane_b32 s48, v253, 18
	v_readlane_b32 s49, v253, 19
	v_readlane_b32 s50, v253, 20
	v_readlane_b32 s51, v253, 21
	v_readlane_b32 s52, v253, 22
	v_readlane_b32 s53, v253, 23
	v_readlane_b32 s54, v253, 24
	v_readlane_b32 s55, v253, 25
	v_readlane_b32 s56, v253, 26
	v_readlane_b32 s57, v253, 27
	v_readlane_b32 s58, v253, 28
	v_readlane_b32 s59, v253, 29
	v_readlane_b32 s60, v253, 30
	v_readlane_b32 s61, v253, 31
	v_readlane_b32 s62, v253, 32
	v_readlane_b32 s63, v253, 33
	v_or_b32_e32 v0, s10, v153
	v_lshlrev_b32_e32 v0, 2, v0
	v_add_u32_e32 v130, s4, v152
	v_lshlrev_b32_e32 v50, 3, v130
	v_lshlrev_b32_e32 v130, 12, v130
	v_add_u32_e32 v130, v130, v0
	v_add_u32_e32 v131, s4, v154
	v_lshlrev_b32_e32 v54, 3, v131
	v_lshlrev_b32_e32 v131, 12, v131
	v_add_u32_e32 v131, v131, v0
	v_add_u32_e32 v132, s4, v155
	v_lshlrev_b32_e32 v58, 3, v132
	v_lshlrev_b32_e32 v132, 12, v132
	v_add_u32_e32 v132, v132, v0
	v_add_u32_e32 v133, s4, v156
	v_lshlrev_b32_e32 v62, 3, v133
	v_lshlrev_b32_e32 v133, 12, v133
	v_add_u32_e32 v133, v133, v0
	s_mov_b32 s10, 0x3fb504f3
	s_cmp_lg_u64 s[40:41], 0
	s_cbranch_scc0 .Lepi_ln_157
	global_load_dwordx4 v[2:5], v130, s[40:41]
	global_load_dwordx4 v[18:21], v130, s[40:41] offset:16
	global_load_dwordx4 v[34:37], v130, s[40:41] offset:128
	global_load_dwordx4 v[50:53], v130, s[40:41] offset:144
	global_load_dwordx4 v[6:9], v131, s[40:41]
	global_load_dwordx4 v[22:25], v131, s[40:41] offset:16
	global_load_dwordx4 v[38:41], v131, s[40:41] offset:128
	global_load_dwordx4 v[54:57], v131, s[40:41] offset:144
	global_load_dwordx4 v[10:13], v132, s[40:41]
	global_load_dwordx4 v[26:29], v132, s[40:41] offset:16
	global_load_dwordx4 v[42:45], v132, s[40:41] offset:128
	global_load_dwordx4 v[58:61], v132, s[40:41] offset:144
	global_load_dwordx4 v[14:17], v133, s[40:41]
	global_load_dwordx4 v[30:33], v133, s[40:41] offset:16
	global_load_dwordx4 v[46:49], v133, s[40:41] offset:128
	global_load_dwordx4 v[62:65], v133, s[40:41] offset:144
	s_waitcnt vmcnt(15)
	v_pk_fma_f32 v[126:127], v[2:3], s[10:11], v[126:127] op_sel_hi:[1,0,1]
	v_pk_fma_f32 v[128:129], v[4:5], s[10:11], v[128:129] op_sel_hi:[1,0,1]
	global_store_dwordx4 v130, v[126:129], s[62:63]
	s_waitcnt vmcnt(15)
	v_pk_fma_f32 v[122:123], v[18:19], s[10:11], v[122:123] op_sel_hi:[1,0,1]
	v_pk_fma_f32 v[124:125], v[20:21], s[10:11], v[124:125] op_sel_hi:[1,0,1]
	global_store_dwordx4 v130, v[122:125], s[62:63] offset:16
	s_waitcnt vmcnt(15)
	v_pk_fma_f32 v[118:119], v[34:35], s[10:11], v[118:119] op_sel_hi:[1,0,1]
	v_pk_fma_f32 v[120:121], v[36:37], s[10:11], v[120:121] op_sel_hi:[1,0,1]
	global_store_dwordx4 v130, v[118:121], s[62:63] offset:128
	s_waitcnt vmcnt(15)
	v_pk_fma_f32 v[114:115], v[50:51], s[10:11], v[114:115] op_sel_hi:[1,0,1]
	v_pk_fma_f32 v[116:117], v[52:53], s[10:11], v[116:117] op_sel_hi:[1,0,1]
	global_store_dwordx4 v130, v[114:117], s[62:63] offset:144
	s_waitcnt vmcnt(15)
	v_pk_fma_f32 v[110:111], v[6:7], s[10:11], v[110:111] op_sel_hi:[1,0,1]
	v_pk_fma_f32 v[112:113], v[8:9], s[10:11], v[112:113] op_sel_hi:[1,0,1]
	global_store_dwordx4 v131, v[110:113], s[62:63]
	s_waitcnt vmcnt(15)
	v_pk_fma_f32 v[106:107], v[22:23], s[10:11], v[106:107] op_sel_hi:[1,0,1]
	v_pk_fma_f32 v[108:109], v[24:25], s[10:11], v[108:109] op_sel_hi:[1,0,1]
	global_store_dwordx4 v131, v[106:109], s[62:63] offset:16
	s_waitcnt vmcnt(15)
	v_pk_fma_f32 v[102:103], v[38:39], s[10:11], v[102:103] op_sel_hi:[1,0,1]
	v_pk_fma_f32 v[104:105], v[40:41], s[10:11], v[104:105] op_sel_hi:[1,0,1]
	global_store_dwordx4 v131, v[102:105], s[62:63] offset:128
	s_waitcnt vmcnt(15)
	v_pk_fma_f32 v[98:99], v[54:55], s[10:11], v[98:99] op_sel_hi:[1,0,1]
	v_pk_fma_f32 v[100:101], v[56:57], s[10:11], v[100:101] op_sel_hi:[1,0,1]
	global_store_dwordx4 v131, v[98:101], s[62:63] offset:144
	s_waitcnt vmcnt(15)
	v_pk_fma_f32 v[94:95], v[10:11], s[10:11], v[94:95] op_sel_hi:[1,0,1]
	v_pk_fma_f32 v[96:97], v[12:13], s[10:11], v[96:97] op_sel_hi:[1,0,1]
	global_store_dwordx4 v132, v[94:97], s[62:63]
	s_waitcnt vmcnt(15)
	v_pk_fma_f32 v[90:91], v[26:27], s[10:11], v[90:91] op_sel_hi:[1,0,1]
	v_pk_fma_f32 v[92:93], v[28:29], s[10:11], v[92:93] op_sel_hi:[1,0,1]
	global_store_dwordx4 v132, v[90:93], s[62:63] offset:16
	s_waitcnt vmcnt(15)
	v_pk_fma_f32 v[86:87], v[42:43], s[10:11], v[86:87] op_sel_hi:[1,0,1]
	v_pk_fma_f32 v[88:89], v[44:45], s[10:11], v[88:89] op_sel_hi:[1,0,1]
	global_store_dwordx4 v132, v[86:89], s[62:63] offset:128
	s_waitcnt vmcnt(15)
	v_pk_fma_f32 v[82:83], v[58:59], s[10:11], v[82:83] op_sel_hi:[1,0,1]
	v_pk_fma_f32 v[84:85], v[60:61], s[10:11], v[84:85] op_sel_hi:[1,0,1]
	global_store_dwordx4 v132, v[82:85], s[62:63] offset:144
	s_waitcnt vmcnt(15)
	v_pk_fma_f32 v[78:79], v[14:15], s[10:11], v[78:79] op_sel_hi:[1,0,1]
	v_pk_fma_f32 v[80:81], v[16:17], s[10:11], v[80:81] op_sel_hi:[1,0,1]
	global_store_dwordx4 v133, v[78:81], s[62:63]
	s_waitcnt vmcnt(15)
	v_pk_fma_f32 v[74:75], v[30:31], s[10:11], v[74:75] op_sel_hi:[1,0,1]
	v_pk_fma_f32 v[76:77], v[32:33], s[10:11], v[76:77] op_sel_hi:[1,0,1]
	global_store_dwordx4 v133, v[74:77], s[62:63] offset:16
	s_waitcnt vmcnt(15)
	v_pk_fma_f32 v[70:71], v[46:47], s[10:11], v[70:71] op_sel_hi:[1,0,1]
	v_pk_fma_f32 v[72:73], v[48:49], s[10:11], v[72:73] op_sel_hi:[1,0,1]
	global_store_dwordx4 v133, v[70:73], s[62:63] offset:128
	s_waitcnt vmcnt(15)
	v_pk_fma_f32 v[66:67], v[62:63], s[10:11], v[66:67] op_sel_hi:[1,0,1]
	v_pk_fma_f32 v[68:69], v[64:65], s[10:11], v[68:69] op_sel_hi:[1,0,1]
	global_store_dwordx4 v133, v[66:69], s[62:63] offset:144
	s_branch .Lepi_done_157
.Lepi_ln_157:
	global_load_dwordx2 v[134:135], v50, s[0:1]
	global_load_dwordx2 v[136:137], v54, s[0:1]
	global_load_dwordx2 v[140:141], v58, s[0:1]
	global_load_dwordx2 v[142:143], v62, s[0:1]
	global_load_dwordx4 v[144:147], v0, s[58:59]
	global_load_dwordx4 v[234:237], v0, s[60:61]
	global_load_dwordx4 v[148:151], v0, s[58:59] offset:16
	global_load_dwordx4 v[238:241], v0, s[60:61] offset:16
	global_load_dwordx4 v[158:161], v0, s[58:59] offset:128
	global_load_dwordx4 v[242:245], v0, s[60:61] offset:128
	global_load_dwordx4 v[162:165], v0, s[58:59] offset:144
	global_load_dwordx4 v[246:249], v0, s[60:61] offset:144
	global_load_dwordx4 v[2:5], v130, s[62:63]
	global_load_dwordx4 v[18:21], v130, s[62:63] offset:16
	global_load_dwordx4 v[34:37], v130, s[62:63] offset:128
	global_load_dwordx4 v[50:53], v130, s[62:63] offset:144
	global_load_dwordx4 v[6:9], v131, s[62:63]
	global_load_dwordx4 v[22:25], v131, s[62:63] offset:16
	global_load_dwordx4 v[38:41], v131, s[62:63] offset:128
	global_load_dwordx4 v[54:57], v131, s[62:63] offset:144
	global_load_dwordx4 v[10:13], v132, s[62:63]
	global_load_dwordx4 v[26:29], v132, s[62:63] offset:16
	global_load_dwordx4 v[42:45], v132, s[62:63] offset:128
	global_load_dwordx4 v[58:61], v132, s[62:63] offset:144
	global_load_dwordx4 v[14:17], v133, s[62:63]
	global_load_dwordx4 v[30:33], v133, s[62:63] offset:16
	global_load_dwordx4 v[46:49], v133, s[62:63] offset:128
	global_load_dwordx4 v[62:65], v133, s[62:63] offset:144
	s_waitcnt vmcnt(15)
	v_pk_add_f32 v[2:3], v[2:3], v[134:135] op_sel_hi:[1,0] neg_lo:[0,1] neg_hi:[0,1]
	v_pk_add_f32 v[4:5], v[4:5], v[134:135] op_sel_hi:[1,0] neg_lo:[0,1] neg_hi:[0,1]
	v_pk_mul_f32 v[2:3], v[2:3], v[134:135] op_sel:[0,1]
	v_pk_mul_f32 v[4:5], v[4:5], v[134:135] op_sel:[0,1]
	v_pk_fma_f32 v[2:3], v[2:3], v[144:145], v[234:235]
	v_pk_fma_f32 v[4:5], v[4:5], v[146:147], v[236:237]
	v_pk_fma_f32 v[126:127], v[2:3], s[10:11], v[126:127] op_sel_hi:[1,0,1]
	v_pk_fma_f32 v[128:129], v[4:5], s[10:11], v[128:129] op_sel_hi:[1,0,1]
	global_store_dwordx4 v130, v[126:129], s[62:63]
	s_waitcnt vmcnt(15)
	v_pk_add_f32 v[18:19], v[18:19], v[134:135] op_sel_hi:[1,0] neg_lo:[0,1] neg_hi:[0,1]
	v_pk_add_f32 v[20:21], v[20:21], v[134:135] op_sel_hi:[1,0] neg_lo:[0,1] neg_hi:[0,1]
	v_pk_mul_f32 v[18:19], v[18:19], v[134:135] op_sel:[0,1]
	v_pk_mul_f32 v[20:21], v[20:21], v[134:135] op_sel:[0,1]
	v_pk_fma_f32 v[18:19], v[18:19], v[148:149], v[238:239]
	v_pk_fma_f32 v[20:21], v[20:21], v[150:151], v[240:241]
	v_pk_fma_f32 v[122:123], v[18:19], s[10:11], v[122:123] op_sel_hi:[1,0,1]
	v_pk_fma_f32 v[124:125], v[20:21], s[10:11], v[124:125] op_sel_hi:[1,0,1]
	global_store_dwordx4 v130, v[122:125], s[62:63] offset:16
	s_waitcnt vmcnt(15)
	v_pk_add_f32 v[34:35], v[34:35], v[134:135] op_sel_hi:[1,0] neg_lo:[0,1] neg_hi:[0,1]
	v_pk_add_f32 v[36:37], v[36:37], v[134:135] op_sel_hi:[1,0] neg_lo:[0,1] neg_hi:[0,1]
	v_pk_mul_f32 v[34:35], v[34:35], v[134:135] op_sel:[0,1]
	v_pk_mul_f32 v[36:37], v[36:37], v[134:135] op_sel:[0,1]
	v_pk_fma_f32 v[34:35], v[34:35], v[158:159], v[242:243]
	v_pk_fma_f32 v[36:37], v[36:37], v[160:161], v[244:245]
	v_pk_fma_f32 v[118:119], v[34:35], s[10:11], v[118:119] op_sel_hi:[1,0,1]
	v_pk_fma_f32 v[120:121], v[36:37], s[10:11], v[120:121] op_sel_hi:[1,0,1]
	global_store_dwordx4 v130, v[118:121], s[62:63] offset:128
	s_waitcnt vmcnt(15)
	v_pk_add_f32 v[50:51], v[50:51], v[134:135] op_sel_hi:[1,0] neg_lo:[0,1] neg_hi:[0,1]
	v_pk_add_f32 v[52:53], v[52:53], v[134:135] op_sel_hi:[1,0] neg_lo:[0,1] neg_hi:[0,1]
	v_pk_mul_f32 v[50:51], v[50:51], v[134:135] op_sel:[0,1]
	v_pk_mul_f32 v[52:53], v[52:53], v[134:135] op_sel:[0,1]
	v_pk_fma_f32 v[50:51], v[50:51], v[162:163], v[246:247]
	v_pk_fma_f32 v[52:53], v[52:53], v[164:165], v[248:249]
	v_pk_fma_f32 v[114:115], v[50:51], s[10:11], v[114:115] op_sel_hi:[1,0,1]
	v_pk_fma_f32 v[116:117], v[52:53], s[10:11], v[116:117] op_sel_hi:[1,0,1]
	global_store_dwordx4 v130, v[114:117], s[62:63] offset:144
	s_waitcnt vmcnt(15)
	v_pk_add_f32 v[6:7], v[6:7], v[136:137] op_sel_hi:[1,0] neg_lo:[0,1] neg_hi:[0,1]
	v_pk_add_f32 v[8:9], v[8:9], v[136:137] op_sel_hi:[1,0] neg_lo:[0,1] neg_hi:[0,1]
	v_pk_mul_f32 v[6:7], v[6:7], v[136:137] op_sel:[0,1]
	v_pk_mul_f32 v[8:9], v[8:9], v[136:137] op_sel:[0,1]
	v_pk_fma_f32 v[6:7], v[6:7], v[144:145], v[234:235]
	v_pk_fma_f32 v[8:9], v[8:9], v[146:147], v[236:237]
	v_pk_fma_f32 v[110:111], v[6:7], s[10:11], v[110:111] op_sel_hi:[1,0,1]
	v_pk_fma_f32 v[112:113], v[8:9], s[10:11], v[112:113] op_sel_hi:[1,0,1]
	global_store_dwordx4 v131, v[110:113], s[62:63]
	s_waitcnt vmcnt(15)
	v_pk_add_f32 v[22:23], v[22:23], v[136:137] op_sel_hi:[1,0] neg_lo:[0,1] neg_hi:[0,1]
	v_pk_add_f32 v[24:25], v[24:25], v[136:137] op_sel_hi:[1,0] neg_lo:[0,1] neg_hi:[0,1]
	v_pk_mul_f32 v[22:23], v[22:23], v[136:137] op_sel:[0,1]
	v_pk_mul_f32 v[24:25], v[24:25], v[136:137] op_sel:[0,1]
	v_pk_fma_f32 v[22:23], v[22:23], v[148:149], v[238:239]
	v_pk_fma_f32 v[24:25], v[24:25], v[150:151], v[240:241]
	v_pk_fma_f32 v[106:107], v[22:23], s[10:11], v[106:107] op_sel_hi:[1,0,1]
	v_pk_fma_f32 v[108:109], v[24:25], s[10:11], v[108:109] op_sel_hi:[1,0,1]
	global_store_dwordx4 v131, v[106:109], s[62:63] offset:16
	s_waitcnt vmcnt(15)
	v_pk_add_f32 v[38:39], v[38:39], v[136:137] op_sel_hi:[1,0] neg_lo:[0,1] neg_hi:[0,1]
	v_pk_add_f32 v[40:41], v[40:41], v[136:137] op_sel_hi:[1,0] neg_lo:[0,1] neg_hi:[0,1]
	v_pk_mul_f32 v[38:39], v[38:39], v[136:137] op_sel:[0,1]
	v_pk_mul_f32 v[40:41], v[40:41], v[136:137] op_sel:[0,1]
	v_pk_fma_f32 v[38:39], v[38:39], v[158:159], v[242:243]
	v_pk_fma_f32 v[40:41], v[40:41], v[160:161], v[244:245]
	v_pk_fma_f32 v[102:103], v[38:39], s[10:11], v[102:103] op_sel_hi:[1,0,1]
	v_pk_fma_f32 v[104:105], v[40:41], s[10:11], v[104:105] op_sel_hi:[1,0,1]
	global_store_dwordx4 v131, v[102:105], s[62:63] offset:128
	s_waitcnt vmcnt(15)
	v_pk_add_f32 v[54:55], v[54:55], v[136:137] op_sel_hi:[1,0] neg_lo:[0,1] neg_hi:[0,1]
	v_pk_add_f32 v[56:57], v[56:57], v[136:137] op_sel_hi:[1,0] neg_lo:[0,1] neg_hi:[0,1]
	v_pk_mul_f32 v[54:55], v[54:55], v[136:137] op_sel:[0,1]
	v_pk_mul_f32 v[56:57], v[56:57], v[136:137] op_sel:[0,1]
	v_pk_fma_f32 v[54:55], v[54:55], v[162:163], v[246:247]
	v_pk_fma_f32 v[56:57], v[56:57], v[164:165], v[248:249]
	v_pk_fma_f32 v[98:99], v[54:55], s[10:11], v[98:99] op_sel_hi:[1,0,1]
	v_pk_fma_f32 v[100:101], v[56:57], s[10:11], v[100:101] op_sel_hi:[1,0,1]
	global_store_dwordx4 v131, v[98:101], s[62:63] offset:144
	s_waitcnt vmcnt(15)
	v_pk_add_f32 v[10:11], v[10:11], v[140:141] op_sel_hi:[1,0] neg_lo:[0,1] neg_hi:[0,1]
	v_pk_add_f32 v[12:13], v[12:13], v[140:141] op_sel_hi:[1,0] neg_lo:[0,1] neg_hi:[0,1]
	v_pk_mul_f32 v[10:11], v[10:11], v[140:141] op_sel:[0,1]
	v_pk_mul_f32 v[12:13], v[12:13], v[140:141] op_sel:[0,1]
	v_pk_fma_f32 v[10:11], v[10:11], v[144:145], v[234:235]
	v_pk_fma_f32 v[12:13], v[12:13], v[146:147], v[236:237]
	v_pk_fma_f32 v[94:95], v[10:11], s[10:11], v[94:95] op_sel_hi:[1,0,1]
	v_pk_fma_f32 v[96:97], v[12:13], s[10:11], v[96:97] op_sel_hi:[1,0,1]
	global_store_dwordx4 v132, v[94:97], s[62:63]
	s_waitcnt vmcnt(15)
	v_pk_add_f32 v[26:27], v[26:27], v[140:141] op_sel_hi:[1,0] neg_lo:[0,1] neg_hi:[0,1]
	v_pk_add_f32 v[28:29], v[28:29], v[140:141] op_sel_hi:[1,0] neg_lo:[0,1] neg_hi:[0,1]
	v_pk_mul_f32 v[26:27], v[26:27], v[140:141] op_sel:[0,1]
	v_pk_mul_f32 v[28:29], v[28:29], v[140:141] op_sel:[0,1]
	v_pk_fma_f32 v[26:27], v[26:27], v[148:149], v[238:239]
	v_pk_fma_f32 v[28:29], v[28:29], v[150:151], v[240:241]
	v_pk_fma_f32 v[90:91], v[26:27], s[10:11], v[90:91] op_sel_hi:[1,0,1]
	v_pk_fma_f32 v[92:93], v[28:29], s[10:11], v[92:93] op_sel_hi:[1,0,1]
	global_store_dwordx4 v132, v[90:93], s[62:63] offset:16
	s_waitcnt vmcnt(15)
	v_pk_add_f32 v[42:43], v[42:43], v[140:141] op_sel_hi:[1,0] neg_lo:[0,1] neg_hi:[0,1]
	v_pk_add_f32 v[44:45], v[44:45], v[140:141] op_sel_hi:[1,0] neg_lo:[0,1] neg_hi:[0,1]
	v_pk_mul_f32 v[42:43], v[42:43], v[140:141] op_sel:[0,1]
	v_pk_mul_f32 v[44:45], v[44:45], v[140:141] op_sel:[0,1]
	v_pk_fma_f32 v[42:43], v[42:43], v[158:159], v[242:243]
	v_pk_fma_f32 v[44:45], v[44:45], v[160:161], v[244:245]
	v_pk_fma_f32 v[86:87], v[42:43], s[10:11], v[86:87] op_sel_hi:[1,0,1]
	v_pk_fma_f32 v[88:89], v[44:45], s[10:11], v[88:89] op_sel_hi:[1,0,1]
	global_store_dwordx4 v132, v[86:89], s[62:63] offset:128
	s_waitcnt vmcnt(15)
	v_pk_add_f32 v[58:59], v[58:59], v[140:141] op_sel_hi:[1,0] neg_lo:[0,1] neg_hi:[0,1]
	v_pk_add_f32 v[60:61], v[60:61], v[140:141] op_sel_hi:[1,0] neg_lo:[0,1] neg_hi:[0,1]
	v_pk_mul_f32 v[58:59], v[58:59], v[140:141] op_sel:[0,1]
	v_pk_mul_f32 v[60:61], v[60:61], v[140:141] op_sel:[0,1]
	v_pk_fma_f32 v[58:59], v[58:59], v[162:163], v[246:247]
	v_pk_fma_f32 v[60:61], v[60:61], v[164:165], v[248:249]
	v_pk_fma_f32 v[82:83], v[58:59], s[10:11], v[82:83] op_sel_hi:[1,0,1]
	v_pk_fma_f32 v[84:85], v[60:61], s[10:11], v[84:85] op_sel_hi:[1,0,1]
	global_store_dwordx4 v132, v[82:85], s[62:63] offset:144
	s_waitcnt vmcnt(15)
	v_pk_add_f32 v[14:15], v[14:15], v[142:143] op_sel_hi:[1,0] neg_lo:[0,1] neg_hi:[0,1]
	v_pk_add_f32 v[16:17], v[16:17], v[142:143] op_sel_hi:[1,0] neg_lo:[0,1] neg_hi:[0,1]
	v_pk_mul_f32 v[14:15], v[14:15], v[142:143] op_sel:[0,1]
	v_pk_mul_f32 v[16:17], v[16:17], v[142:143] op_sel:[0,1]
	v_pk_fma_f32 v[14:15], v[14:15], v[144:145], v[234:235]
	v_pk_fma_f32 v[16:17], v[16:17], v[146:147], v[236:237]
	v_pk_fma_f32 v[78:79], v[14:15], s[10:11], v[78:79] op_sel_hi:[1,0,1]
	v_pk_fma_f32 v[80:81], v[16:17], s[10:11], v[80:81] op_sel_hi:[1,0,1]
	global_store_dwordx4 v133, v[78:81], s[62:63]
	s_waitcnt vmcnt(15)
	v_pk_add_f32 v[30:31], v[30:31], v[142:143] op_sel_hi:[1,0] neg_lo:[0,1] neg_hi:[0,1]
	v_pk_add_f32 v[32:33], v[32:33], v[142:143] op_sel_hi:[1,0] neg_lo:[0,1] neg_hi:[0,1]
	v_pk_mul_f32 v[30:31], v[30:31], v[142:143] op_sel:[0,1]
	v_pk_mul_f32 v[32:33], v[32:33], v[142:143] op_sel:[0,1]
	v_pk_fma_f32 v[30:31], v[30:31], v[148:149], v[238:239]
	v_pk_fma_f32 v[32:33], v[32:33], v[150:151], v[240:241]
	v_pk_fma_f32 v[74:75], v[30:31], s[10:11], v[74:75] op_sel_hi:[1,0,1]
	v_pk_fma_f32 v[76:77], v[32:33], s[10:11], v[76:77] op_sel_hi:[1,0,1]
	global_store_dwordx4 v133, v[74:77], s[62:63] offset:16
	s_waitcnt vmcnt(15)
	v_pk_add_f32 v[46:47], v[46:47], v[142:143] op_sel_hi:[1,0] neg_lo:[0,1] neg_hi:[0,1]
	v_pk_add_f32 v[48:49], v[48:49], v[142:143] op_sel_hi:[1,0] neg_lo:[0,1] neg_hi:[0,1]
	v_pk_mul_f32 v[46:47], v[46:47], v[142:143] op_sel:[0,1]
	v_pk_mul_f32 v[48:49], v[48:49], v[142:143] op_sel:[0,1]
	v_pk_fma_f32 v[46:47], v[46:47], v[158:159], v[242:243]
	v_pk_fma_f32 v[48:49], v[48:49], v[160:161], v[244:245]
	v_pk_fma_f32 v[70:71], v[46:47], s[10:11], v[70:71] op_sel_hi:[1,0,1]
	v_pk_fma_f32 v[72:73], v[48:49], s[10:11], v[72:73] op_sel_hi:[1,0,1]
	global_store_dwordx4 v133, v[70:73], s[62:63] offset:128
	s_waitcnt vmcnt(15)
	v_pk_add_f32 v[62:63], v[62:63], v[142:143] op_sel_hi:[1,0] neg_lo:[0,1] neg_hi:[0,1]
	v_pk_add_f32 v[64:65], v[64:65], v[142:143] op_sel_hi:[1,0] neg_lo:[0,1] neg_hi:[0,1]
	v_pk_mul_f32 v[62:63], v[62:63], v[142:143] op_sel:[0,1]
	v_pk_mul_f32 v[64:65], v[64:65], v[142:143] op_sel:[0,1]
	v_pk_fma_f32 v[62:63], v[62:63], v[162:163], v[246:247]
	v_pk_fma_f32 v[64:65], v[64:65], v[164:165], v[248:249]
	v_pk_fma_f32 v[66:67], v[62:63], s[10:11], v[66:67] op_sel_hi:[1,0,1]
	v_pk_fma_f32 v[68:69], v[64:65], s[10:11], v[68:69] op_sel_hi:[1,0,1]
	global_store_dwordx4 v133, v[66:69], s[62:63] offset:144
